# GEMM K-loops: one weight-tile LDS-DMA piece moved from the 6-piece load segment to the following 2-piece segment (5+3 instead of 6+2), vmcnt 8->7 in that segment
# speedup vs baseline: 1.0069x; 1.0069x over previous
.LBB0_323:
	ds_read_b128 v[96:99], v209
	ds_read_b128 v[100:103], v209 offset:1024
	ds_read_b128 v[120:123], v209 offset:2048
	ds_read_b128 v[124:127], v209 offset:3072
	ds_read_b128 v[144:147], v210
	ds_read_b128 v[148:151], v210 offset:1024
	ds_read_b128 v[152:155], v210 offset:2048
	ds_read_b128 v[156:159], v210 offset:3072
	s_add_u32 s8, s6, 0xfffc0080
	s_addc_u32 s9, s7, -1
	s_cmp_eq_u32 s78, 12
	s_cselect_b32 s51, s18, s9
	s_cselect_b32 s50, s43, s8
	s_cselect_b32 s9, s45, s57
	s_cselect_b32 s8, s55, s56
	v_lshl_add_u64 v[206:207], s[6:7], 0, v[170:171]
	s_add_i32 m0, s17, 0xc000
	ds_read_b128 v[178:181], v211
	ds_read_b128 v[182:185], v211 offset:1024
	ds_read_b128 v[186:189], v211 offset:2048
	ds_read_b128 v[190:193], v211 offset:3072
	ds_read_b128 v[194:197], v211 offset:4096
	ds_read_b128 v[198:201], v211 offset:5120
	ds_read_b128 v[202:205], v211 offset:6144
	ds_read_b128 v[218:221], v211 offset:7168
	global_load_lds_dwordx4 v[206:207], off
	v_lshl_add_u64 v[206:207], s[6:7], 0, v[172:173]
	s_add_i32 m0, s17, 0xe000
	s_nop 0
	global_load_lds_dwordx4 v[206:207], off
	s_waitcnt vmcnt(8)
	s_waitcnt lgkmcnt(0)
	s_barrier
	s_setprio 1
	s_waitcnt lgkmcnt(0)
	v_mfma_f32_16x16x32_bf16 v[140:143], v[96:99], v[178:181], v[140:143]
	v_mfma_f32_16x16x32_bf16 v[136:139], v[120:123], v[178:181], v[136:139]
	v_mfma_f32_16x16x32_bf16 v[116:119], v[96:99], v[186:189], v[116:119]
	v_mfma_f32_16x16x32_bf16 v[112:115], v[120:123], v[186:189], v[112:115]
	v_mfma_f32_16x16x32_bf16 v[92:95], v[96:99], v[194:197], v[92:95]
	v_mfma_f32_16x16x32_bf16 v[88:91], v[120:123], v[194:197], v[88:91]
	v_mfma_f32_16x16x32_bf16 v[76:79], v[96:99], v[202:205], v[76:79]
	v_mfma_f32_16x16x32_bf16 v[72:75], v[120:123], v[202:205], v[72:75]
	v_mfma_f32_16x16x32_bf16 v[140:143], v[100:103], v[182:185], v[140:143]
	v_mfma_f32_16x16x32_bf16 v[136:139], v[124:127], v[182:185], v[136:139]
	v_mfma_f32_16x16x32_bf16 v[116:119], v[100:103], v[190:193], v[116:119]
	v_mfma_f32_16x16x32_bf16 v[112:115], v[124:127], v[190:193], v[112:115]
	v_mfma_f32_16x16x32_bf16 v[92:95], v[100:103], v[198:201], v[92:95]
	v_mfma_f32_16x16x32_bf16 v[88:91], v[124:127], v[198:201], v[88:91]
	v_mfma_f32_16x16x32_bf16 v[76:79], v[100:103], v[218:221], v[76:79]
	v_mfma_f32_16x16x32_bf16 v[72:75], v[124:127], v[218:221], v[72:75]
	s_setprio 0
	s_setprio 1
	v_mfma_f32_16x16x32_bf16 v[132:135], v[144:147], v[178:181], v[132:135]
	v_mfma_f32_16x16x32_bf16 v[128:131], v[152:155], v[178:181], v[128:131]
	v_mfma_f32_16x16x32_bf16 v[108:111], v[144:147], v[186:189], v[108:111]
	v_mfma_f32_16x16x32_bf16 v[104:107], v[152:155], v[186:189], v[104:107]
	v_mfma_f32_16x16x32_bf16 v[84:87], v[144:147], v[194:197], v[84:87]
	v_mfma_f32_16x16x32_bf16 v[80:83], v[152:155], v[194:197], v[80:83]
	v_mfma_f32_16x16x32_bf16 v[68:71], v[144:147], v[202:205], v[68:71]
	v_mfma_f32_16x16x32_bf16 v[64:67], v[152:155], v[202:205], v[64:67]
	v_mfma_f32_16x16x32_bf16 v[132:135], v[148:151], v[182:185], v[132:135]
	v_mfma_f32_16x16x32_bf16 v[128:131], v[156:159], v[182:185], v[128:131]
	v_mfma_f32_16x16x32_bf16 v[108:111], v[148:151], v[190:193], v[108:111]
	v_mfma_f32_16x16x32_bf16 v[104:107], v[156:159], v[190:193], v[104:107]
	s_setprio 2
	s_barrier
	v_mfma_f32_16x16x32_bf16 v[84:87], v[148:151], v[198:201], v[84:87]
	v_mfma_f32_16x16x32_bf16 v[80:83], v[156:159], v[198:201], v[80:83]
	v_mfma_f32_16x16x32_bf16 v[68:71], v[148:151], v[218:221], v[68:71]
	v_mfma_f32_16x16x32_bf16 v[64:67], v[156:159], v[218:221], v[64:67]
	s_setprio 0
	s_add_i32 s79, s73, s61
	v_lshl_add_u64 v[206:207], s[8:9], 0, v[162:163]
	s_mov_b32 m0, s79
	ds_read_b128 v[178:181], v211 offset:16384
	ds_read_b128 v[182:185], v211 offset:17408
	ds_read_b128 v[186:189], v211 offset:18432
	ds_read_b128 v[190:193], v211 offset:19456
	ds_read_b128 v[194:197], v211 offset:20480
	ds_read_b128 v[198:201], v211 offset:21504
	ds_read_b128 v[202:205], v211 offset:22528
	ds_read_b128 v[218:221], v211 offset:23552
	global_load_lds_dwordx4 v[206:207], off
	s_add_i32 m0, s79, 0x2000
	s_add_u32 s80, s8, 0x40000
	v_lshl_add_u64 v[222:223], s[8:9], 0, v[166:167]
	s_addc_u32 s81, s9, 0
	s_add_i32 s79, s74, s61
	global_load_lds_dwordx4 v[222:223], off
	v_lshl_add_u64 v[224:225], s[80:81], 0, v[162:163]
	s_mov_b32 m0, s79
	v_lshl_add_u64 v[226:227], s[50:51], 0, v[164:165]
	global_load_lds_dwordx4 v[224:225], off
	v_lshl_add_u64 v[224:225], s[50:51], 0, v[160:161]
	s_mov_b32 m0, s17
	s_nop 0
	global_load_lds_dwordx4 v[224:225], off
	s_mov_b32 m0, s62
	s_nop 0
	global_load_lds_dwordx4 v[226:227], off
	s_waitcnt vmcnt(7)
	s_waitcnt lgkmcnt(0)
	s_barrier
	s_setprio 1
	s_waitcnt lgkmcnt(0)
	v_mfma_f32_16x16x32_bf16 v[60:63], v[96:99], v[178:181], v[60:63]
	v_mfma_f32_16x16x32_bf16 v[56:59], v[120:123], v[178:181], v[56:59]
	v_mfma_f32_16x16x32_bf16 v[44:47], v[96:99], v[186:189], v[44:47]
	v_mfma_f32_16x16x32_bf16 v[40:43], v[120:123], v[186:189], v[40:43]
	v_mfma_f32_16x16x32_bf16 v[28:31], v[96:99], v[194:197], v[28:31]
	v_mfma_f32_16x16x32_bf16 v[24:27], v[120:123], v[194:197], v[24:27]
	v_mfma_f32_16x16x32_bf16 v[12:15], v[96:99], v[202:205], v[12:15]
	v_mfma_f32_16x16x32_bf16 v[8:11], v[120:123], v[202:205], v[8:11]
	v_mfma_f32_16x16x32_bf16 v[60:63], v[100:103], v[182:185], v[60:63]
	v_mfma_f32_16x16x32_bf16 v[56:59], v[124:127], v[182:185], v[56:59]
	v_mfma_f32_16x16x32_bf16 v[44:47], v[100:103], v[190:193], v[44:47]
	v_mfma_f32_16x16x32_bf16 v[40:43], v[124:127], v[190:193], v[40:43]
	v_mfma_f32_16x16x32_bf16 v[28:31], v[100:103], v[198:201], v[28:31]
	v_mfma_f32_16x16x32_bf16 v[24:27], v[124:127], v[198:201], v[24:27]
	v_mfma_f32_16x16x32_bf16 v[12:15], v[100:103], v[218:221], v[12:15]
	v_mfma_f32_16x16x32_bf16 v[8:11], v[124:127], v[218:221], v[8:11]
	s_setprio 0
	s_setprio 1
	v_mfma_f32_16x16x32_bf16 v[52:55], v[144:147], v[178:181], v[52:55]
	v_mfma_f32_16x16x32_bf16 v[48:51], v[152:155], v[178:181], v[48:51]
	v_mfma_f32_16x16x32_bf16 v[36:39], v[144:147], v[186:189], v[36:39]
	v_mfma_f32_16x16x32_bf16 v[32:35], v[152:155], v[186:189], v[32:35]
	v_mfma_f32_16x16x32_bf16 v[20:23], v[144:147], v[194:197], v[20:23]
	v_mfma_f32_16x16x32_bf16 v[16:19], v[152:155], v[194:197], v[16:19]
	v_mfma_f32_16x16x32_bf16 v[4:7], v[144:147], v[202:205], v[4:7]
	v_mfma_f32_16x16x32_bf16 v[0:3], v[152:155], v[202:205], v[0:3]
	v_mfma_f32_16x16x32_bf16 v[52:55], v[148:151], v[182:185], v[52:55]
	v_mfma_f32_16x16x32_bf16 v[48:51], v[156:159], v[182:185], v[48:51]
	v_mfma_f32_16x16x32_bf16 v[36:39], v[148:151], v[190:193], v[36:39]
	v_mfma_f32_16x16x32_bf16 v[32:35], v[156:159], v[190:193], v[32:35]
	s_setprio 2
	s_barrier
	v_mfma_f32_16x16x32_bf16 v[20:23], v[148:151], v[198:201], v[20:23]
	v_mfma_f32_16x16x32_bf16 v[16:19], v[156:159], v[198:201], v[16:19]
	v_mfma_f32_16x16x32_bf16 v[4:7], v[148:151], v[218:221], v[4:7]
	v_mfma_f32_16x16x32_bf16 v[0:3], v[156:159], v[218:221], v[0:3]
	s_setprio 0
	v_lshl_add_u64 v[252:253], s[80:81], 0, v[166:167]
	s_add_i32 m0, s79, 0x2000
	s_nop 0
	global_load_lds_dwordx4 v[252:253], off
	s_add_i32 s79, 0, 0x18000
	s_add_i32 s80, 0, 0x1c000
	v_add_u32_e32 v124, s79, v208
	v_add_u32_e32 v156, s80, v208
	ds_read_b128 v[96:99], v124
	ds_read_b128 v[100:103], v124 offset:1024
	ds_read_b128 v[120:123], v124 offset:2048
	ds_read_b128 v[124:127], v124 offset:3072
	ds_read_b128 v[144:147], v156
	ds_read_b128 v[148:151], v156 offset:1024
	ds_read_b128 v[152:155], v156 offset:2048
	ds_read_b128 v[156:159], v156 offset:3072
	s_add_u32 s50, s50, 0x40000
	s_addc_u32 s51, s51, 0
	s_mov_b32 m0, s63
	v_lshl_add_u64 v[228:229], s[50:51], 0, v[160:161]
	ds_read_b128 v[178:181], v211 offset:32768
	ds_read_b128 v[182:185], v211 offset:33792
	ds_read_b128 v[186:189], v211 offset:34816
	ds_read_b128 v[190:193], v211 offset:35840
	ds_read_b128 v[194:197], v211 offset:36864
	ds_read_b128 v[198:201], v211 offset:37888
	ds_read_b128 v[202:205], v211 offset:38912
	ds_read_b128 v[218:221], v211 offset:39936
	global_load_lds_dwordx4 v[228:229], off
	v_lshl_add_u64 v[228:229], s[50:51], 0, v[164:165]
	s_mov_b32 m0, s64
	s_nop 0
	global_load_lds_dwordx4 v[228:229], off
	s_waitcnt vmcnt(8)
	s_waitcnt lgkmcnt(0)
	s_barrier
	s_setprio 1
	s_waitcnt lgkmcnt(0)
	v_mfma_f32_16x16x32_bf16 v[140:143], v[96:99], v[178:181], v[140:143]
	v_mfma_f32_16x16x32_bf16 v[136:139], v[120:123], v[178:181], v[136:139]
	v_mfma_f32_16x16x32_bf16 v[116:119], v[96:99], v[186:189], v[116:119]
	v_mfma_f32_16x16x32_bf16 v[112:115], v[120:123], v[186:189], v[112:115]
	v_mfma_f32_16x16x32_bf16 v[92:95], v[96:99], v[194:197], v[92:95]
	v_mfma_f32_16x16x32_bf16 v[88:91], v[120:123], v[194:197], v[88:91]
	v_mfma_f32_16x16x32_bf16 v[76:79], v[96:99], v[202:205], v[76:79]
	v_mfma_f32_16x16x32_bf16 v[72:75], v[120:123], v[202:205], v[72:75]
	v_mfma_f32_16x16x32_bf16 v[140:143], v[100:103], v[182:185], v[140:143]
	v_mfma_f32_16x16x32_bf16 v[136:139], v[124:127], v[182:185], v[136:139]
	v_mfma_f32_16x16x32_bf16 v[116:119], v[100:103], v[190:193], v[116:119]
	v_mfma_f32_16x16x32_bf16 v[112:115], v[124:127], v[190:193], v[112:115]
	v_mfma_f32_16x16x32_bf16 v[92:95], v[100:103], v[198:201], v[92:95]
	v_mfma_f32_16x16x32_bf16 v[88:91], v[124:127], v[198:201], v[88:91]
	v_mfma_f32_16x16x32_bf16 v[76:79], v[100:103], v[218:221], v[76:79]
	v_mfma_f32_16x16x32_bf16 v[72:75], v[124:127], v[218:221], v[72:75]
	s_setprio 0
	s_setprio 1
	v_mfma_f32_16x16x32_bf16 v[132:135], v[144:147], v[178:181], v[132:135]
	v_mfma_f32_16x16x32_bf16 v[128:131], v[152:155], v[178:181], v[128:131]
	v_mfma_f32_16x16x32_bf16 v[108:111], v[144:147], v[186:189], v[108:111]
	v_mfma_f32_16x16x32_bf16 v[104:107], v[152:155], v[186:189], v[104:107]
	v_mfma_f32_16x16x32_bf16 v[84:87], v[144:147], v[194:197], v[84:87]
	v_mfma_f32_16x16x32_bf16 v[80:83], v[152:155], v[194:197], v[80:83]
	v_mfma_f32_16x16x32_bf16 v[68:71], v[144:147], v[202:205], v[68:71]
	v_mfma_f32_16x16x32_bf16 v[64:67], v[152:155], v[202:205], v[64:67]
	v_mfma_f32_16x16x32_bf16 v[132:135], v[148:151], v[182:185], v[132:135]
	v_mfma_f32_16x16x32_bf16 v[128:131], v[156:159], v[182:185], v[128:131]
	v_mfma_f32_16x16x32_bf16 v[108:111], v[148:151], v[190:193], v[108:111]
	v_mfma_f32_16x16x32_bf16 v[104:107], v[156:159], v[190:193], v[104:107]
	s_setprio 2
	s_barrier
	v_mfma_f32_16x16x32_bf16 v[84:87], v[148:151], v[198:201], v[84:87]
	v_mfma_f32_16x16x32_bf16 v[80:83], v[156:159], v[198:201], v[80:83]
	v_mfma_f32_16x16x32_bf16 v[68:71], v[148:151], v[218:221], v[68:71]
	v_mfma_f32_16x16x32_bf16 v[64:67], v[156:159], v[218:221], v[64:67]
	s_setprio 0
	s_add_i32 s50, s79, s61
	v_lshl_add_u64 v[206:207], v[206:207], 0, s[36:37]
	s_mov_b32 m0, s50
	ds_read_b128 v[178:181], v211 offset:49152
	ds_read_b128 v[182:185], v211 offset:50176
	ds_read_b128 v[186:189], v211 offset:51200
	ds_read_b128 v[190:193], v211 offset:52224
	ds_read_b128 v[194:197], v211 offset:53248
	ds_read_b128 v[198:201], v211 offset:54272
	ds_read_b128 v[202:205], v211 offset:55296
	ds_read_b128 v[218:221], v211 offset:56320
	global_load_lds_dwordx4 v[206:207], off
	s_add_i32 m0, s50, 0x2000
	s_add_u32 s8, s8, 0x40080
	v_lshl_add_u64 v[206:207], v[222:223], 0, s[36:37]
	s_addc_u32 s9, s9, 0
	s_add_i32 s50, s80, s61
	global_load_lds_dwordx4 v[206:207], off
	v_lshl_add_u64 v[206:207], s[8:9], 0, v[162:163]
	s_mov_b32 m0, s50
	s_nop 0
	global_load_lds_dwordx4 v[206:207], off
	v_lshl_add_u64 v[206:207], s[8:9], 0, v[166:167]
	s_add_i32 m0, s50, 0x2000
	s_nop 0
	global_load_lds_dwordx4 v[206:207], off
	v_lshl_add_u64 v[206:207], v[224:225], 0, s[36:37]
	s_mov_b32 m0, s68
	s_nop 0
	global_load_lds_dwordx4 v[206:207], off
	v_lshl_add_u64 v[206:207], v[226:227], 0, s[36:37]
	s_mov_b32 m0, s69
	s_nop 0
	global_load_lds_dwordx4 v[206:207], off
	s_waitcnt vmcnt(8)
	s_waitcnt lgkmcnt(0)
	s_barrier
	s_setprio 1
	s_waitcnt lgkmcnt(0)
	v_mfma_f32_16x16x32_bf16 v[60:63], v[96:99], v[178:181], v[60:63]
	v_mfma_f32_16x16x32_bf16 v[56:59], v[120:123], v[178:181], v[56:59]
	v_mfma_f32_16x16x32_bf16 v[44:47], v[96:99], v[186:189], v[44:47]
	v_mfma_f32_16x16x32_bf16 v[40:43], v[120:123], v[186:189], v[40:43]
	v_mfma_f32_16x16x32_bf16 v[28:31], v[96:99], v[194:197], v[28:31]
	v_mfma_f32_16x16x32_bf16 v[24:27], v[120:123], v[194:197], v[24:27]
	v_mfma_f32_16x16x32_bf16 v[12:15], v[96:99], v[202:205], v[12:15]
	v_mfma_f32_16x16x32_bf16 v[8:11], v[120:123], v[202:205], v[8:11]
	v_mfma_f32_16x16x32_bf16 v[60:63], v[100:103], v[182:185], v[60:63]
	v_mfma_f32_16x16x32_bf16 v[56:59], v[124:127], v[182:185], v[56:59]
	v_mfma_f32_16x16x32_bf16 v[44:47], v[100:103], v[190:193], v[44:47]
	v_mfma_f32_16x16x32_bf16 v[40:43], v[124:127], v[190:193], v[40:43]
	v_mfma_f32_16x16x32_bf16 v[28:31], v[100:103], v[198:201], v[28:31]
	v_mfma_f32_16x16x32_bf16 v[24:27], v[124:127], v[198:201], v[24:27]
	v_mfma_f32_16x16x32_bf16 v[12:15], v[100:103], v[218:221], v[12:15]
	v_mfma_f32_16x16x32_bf16 v[8:11], v[124:127], v[218:221], v[8:11]
	s_setprio 0
	s_setprio 1
	v_mfma_f32_16x16x32_bf16 v[52:55], v[144:147], v[178:181], v[52:55]
	v_mfma_f32_16x16x32_bf16 v[48:51], v[152:155], v[178:181], v[48:51]
	v_mfma_f32_16x16x32_bf16 v[36:39], v[144:147], v[186:189], v[36:39]
	v_mfma_f32_16x16x32_bf16 v[32:35], v[152:155], v[186:189], v[32:35]
	v_mfma_f32_16x16x32_bf16 v[20:23], v[144:147], v[194:197], v[20:23]
	v_mfma_f32_16x16x32_bf16 v[16:19], v[152:155], v[194:197], v[16:19]
	v_mfma_f32_16x16x32_bf16 v[4:7], v[144:147], v[202:205], v[4:7]
	v_mfma_f32_16x16x32_bf16 v[0:3], v[152:155], v[202:205], v[0:3]
	v_mfma_f32_16x16x32_bf16 v[52:55], v[148:151], v[182:185], v[52:55]
	v_mfma_f32_16x16x32_bf16 v[48:51], v[156:159], v[182:185], v[48:51]
	v_mfma_f32_16x16x32_bf16 v[36:39], v[148:151], v[190:193], v[36:39]
	v_mfma_f32_16x16x32_bf16 v[32:35], v[156:159], v[190:193], v[32:35]
	s_setprio 2
	s_barrier
	v_mfma_f32_16x16x32_bf16 v[20:23], v[148:151], v[198:201], v[20:23]
	v_mfma_f32_16x16x32_bf16 v[16:19], v[156:159], v[198:201], v[16:19]
	v_mfma_f32_16x16x32_bf16 v[4:7], v[148:151], v[218:221], v[4:7]
	v_mfma_f32_16x16x32_bf16 v[0:3], v[156:159], v[218:221], v[0:3]
	s_setprio 0
	s_add_i32 s78, s78, 2
	s_add_u32 s6, s6, 0x100
	s_addc_u32 s7, s7, 0
	s_add_u32 s56, s56, 0x100
	s_addc_u32 s57, s57, 0
	s_cmp_gt_u32 s78, 13
	s_cbranch_scc0 .LBB0_323

.LBB0_784:
	ds_read_b128 v[144:147], v163
	ds_read_b128 v[148:151], v163 offset:1024
	ds_read_b128 v[152:155], v163 offset:2048
	ds_read_b128 v[156:159], v163 offset:3072
	ds_read_b128 v[168:171], v164
	ds_read_b128 v[172:175], v164 offset:1024
	ds_read_b128 v[176:179], v164 offset:2048
	ds_read_b128 v[180:183], v164 offset:3072
	s_add_u32 s38, s36, 0xfffc0080
	s_addc_u32 s39, s37, -1
	s_cmp_eq_u32 s65, 12
	s_cselect_b32 s41, s23, s39
	s_cselect_b32 s40, s31, s38
	s_cselect_b32 s39, s25, s64
	s_cselect_b32 s38, s62, s63
	v_lshl_add_u64 v[160:161], s[36:37], 0, v[136:137]
	s_add_i32 m0, s50, 0xc000
	ds_read_b128 v[184:187], v165
	ds_read_b128 v[188:191], v165 offset:1024
	ds_read_b128 v[192:195], v165 offset:2048
	ds_read_b128 v[196:199], v165 offset:3072
	ds_read_b128 v[200:203], v165 offset:4096
	ds_read_b128 v[204:207], v165 offset:5120
	ds_read_b128 v[208:211], v165 offset:6144
	ds_read_b128 v[212:215], v165 offset:7168
	global_load_lds_dwordx4 v[160:161], off
	v_lshl_add_u64 v[160:161], s[36:37], 0, v[138:139]
	s_add_i32 m0, s50, 0xe000
	s_nop 0
	global_load_lds_dwordx4 v[160:161], off
	s_waitcnt vmcnt(8)
	s_waitcnt lgkmcnt(0)
	s_barrier
	s_setprio 1
	s_waitcnt lgkmcnt(0)
	v_mfma_f32_16x16x32_bf16 v[124:127], v[144:147], v[184:187], v[124:127]
	v_mfma_f32_16x16x32_bf16 v[120:123], v[152:155], v[184:187], v[120:123]
	v_mfma_f32_16x16x32_bf16 v[108:111], v[144:147], v[192:195], v[108:111]
	v_mfma_f32_16x16x32_bf16 v[104:107], v[152:155], v[192:195], v[104:107]
	v_mfma_f32_16x16x32_bf16 v[92:95], v[144:147], v[200:203], v[92:95]
	v_mfma_f32_16x16x32_bf16 v[88:91], v[152:155], v[200:203], v[88:91]
	v_mfma_f32_16x16x32_bf16 v[76:79], v[144:147], v[208:211], v[76:79]
	v_mfma_f32_16x16x32_bf16 v[72:75], v[152:155], v[208:211], v[72:75]
	v_mfma_f32_16x16x32_bf16 v[124:127], v[148:151], v[188:191], v[124:127]
	v_mfma_f32_16x16x32_bf16 v[120:123], v[156:159], v[188:191], v[120:123]
	v_mfma_f32_16x16x32_bf16 v[108:111], v[148:151], v[196:199], v[108:111]
	v_mfma_f32_16x16x32_bf16 v[104:107], v[156:159], v[196:199], v[104:107]
	v_mfma_f32_16x16x32_bf16 v[92:95], v[148:151], v[204:207], v[92:95]
	v_mfma_f32_16x16x32_bf16 v[88:91], v[156:159], v[204:207], v[88:91]
	v_mfma_f32_16x16x32_bf16 v[76:79], v[148:151], v[212:215], v[76:79]
	v_mfma_f32_16x16x32_bf16 v[72:75], v[156:159], v[212:215], v[72:75]
	s_setprio 0
	s_setprio 1
	v_mfma_f32_16x16x32_bf16 v[116:119], v[168:171], v[184:187], v[116:119]
	v_mfma_f32_16x16x32_bf16 v[112:115], v[176:179], v[184:187], v[112:115]
	v_mfma_f32_16x16x32_bf16 v[100:103], v[168:171], v[192:195], v[100:103]
	v_mfma_f32_16x16x32_bf16 v[96:99], v[176:179], v[192:195], v[96:99]
	v_mfma_f32_16x16x32_bf16 v[84:87], v[168:171], v[200:203], v[84:87]
	v_mfma_f32_16x16x32_bf16 v[80:83], v[176:179], v[200:203], v[80:83]
	v_mfma_f32_16x16x32_bf16 v[68:71], v[168:171], v[208:211], v[68:71]
	v_mfma_f32_16x16x32_bf16 v[64:67], v[176:179], v[208:211], v[64:67]
	v_mfma_f32_16x16x32_bf16 v[116:119], v[172:175], v[188:191], v[116:119]
	v_mfma_f32_16x16x32_bf16 v[112:115], v[180:183], v[188:191], v[112:115]
	v_mfma_f32_16x16x32_bf16 v[100:103], v[172:175], v[196:199], v[100:103]
	v_mfma_f32_16x16x32_bf16 v[96:99], v[180:183], v[196:199], v[96:99]
	s_setprio 2
	s_barrier
	v_mfma_f32_16x16x32_bf16 v[84:87], v[172:175], v[204:207], v[84:87]
	v_mfma_f32_16x16x32_bf16 v[80:83], v[180:183], v[204:207], v[80:83]
	v_mfma_f32_16x16x32_bf16 v[68:71], v[172:175], v[212:215], v[68:71]
	v_mfma_f32_16x16x32_bf16 v[64:67], v[180:183], v[212:215], v[64:67]
	s_setprio 0
	s_add_i32 s66, s59, s47
	v_lshl_add_u64 v[160:161], s[38:39], 0, v[132:133]
	s_mov_b32 m0, s66
	ds_read_b128 v[184:187], v165 offset:16384
	ds_read_b128 v[188:191], v165 offset:17408
	ds_read_b128 v[192:195], v165 offset:18432
	ds_read_b128 v[196:199], v165 offset:19456
	ds_read_b128 v[200:203], v165 offset:20480
	ds_read_b128 v[204:207], v165 offset:21504
	ds_read_b128 v[208:211], v165 offset:22528
	ds_read_b128 v[212:215], v165 offset:23552
	global_load_lds_dwordx4 v[160:161], off
	s_add_i32 m0, s66, 0x2000
	s_add_u32 s66, s38, 0x40000
	v_lshl_add_u64 v[216:217], s[38:39], 0, v[128:129]
	s_addc_u32 s67, s39, 0
	s_add_i32 s68, s60, s47
	global_load_lds_dwordx4 v[216:217], off
	v_lshl_add_u64 v[218:219], s[66:67], 0, v[132:133]
	s_mov_b32 m0, s68
	v_lshl_add_u64 v[220:221], s[40:41], 0, v[130:131]
	global_load_lds_dwordx4 v[218:219], off
	v_lshl_add_u64 v[218:219], s[40:41], 0, v[134:135]
	s_mov_b32 m0, s50
	s_nop 0
	global_load_lds_dwordx4 v[218:219], off
	s_mov_b32 m0, s51
	s_nop 0
	global_load_lds_dwordx4 v[220:221], off
	s_waitcnt vmcnt(7)
	s_waitcnt lgkmcnt(0)
	s_barrier
	s_setprio 1
	s_waitcnt lgkmcnt(0)
	v_mfma_f32_16x16x32_bf16 v[60:63], v[144:147], v[184:187], v[60:63]
	v_mfma_f32_16x16x32_bf16 v[56:59], v[152:155], v[184:187], v[56:59]
	v_mfma_f32_16x16x32_bf16 v[44:47], v[144:147], v[192:195], v[44:47]
	v_mfma_f32_16x16x32_bf16 v[40:43], v[152:155], v[192:195], v[40:43]
	v_mfma_f32_16x16x32_bf16 v[28:31], v[144:147], v[200:203], v[28:31]
	v_mfma_f32_16x16x32_bf16 v[24:27], v[152:155], v[200:203], v[24:27]
	v_mfma_f32_16x16x32_bf16 v[12:15], v[144:147], v[208:211], v[12:15]
	v_mfma_f32_16x16x32_bf16 v[8:11], v[152:155], v[208:211], v[8:11]
	v_mfma_f32_16x16x32_bf16 v[60:63], v[148:151], v[188:191], v[60:63]
	v_mfma_f32_16x16x32_bf16 v[56:59], v[156:159], v[188:191], v[56:59]
	v_mfma_f32_16x16x32_bf16 v[44:47], v[148:151], v[196:199], v[44:47]
	v_mfma_f32_16x16x32_bf16 v[40:43], v[156:159], v[196:199], v[40:43]
	v_mfma_f32_16x16x32_bf16 v[28:31], v[148:151], v[204:207], v[28:31]
	v_mfma_f32_16x16x32_bf16 v[24:27], v[156:159], v[204:207], v[24:27]
	v_mfma_f32_16x16x32_bf16 v[12:15], v[148:151], v[212:215], v[12:15]
	v_mfma_f32_16x16x32_bf16 v[8:11], v[156:159], v[212:215], v[8:11]
	s_setprio 0
	s_setprio 1
	v_mfma_f32_16x16x32_bf16 v[52:55], v[168:171], v[184:187], v[52:55]
	v_mfma_f32_16x16x32_bf16 v[48:51], v[176:179], v[184:187], v[48:51]
	v_mfma_f32_16x16x32_bf16 v[36:39], v[168:171], v[192:195], v[36:39]
	v_mfma_f32_16x16x32_bf16 v[32:35], v[176:179], v[192:195], v[32:35]
	v_mfma_f32_16x16x32_bf16 v[20:23], v[168:171], v[200:203], v[20:23]
	v_mfma_f32_16x16x32_bf16 v[16:19], v[176:179], v[200:203], v[16:19]
	v_mfma_f32_16x16x32_bf16 v[4:7], v[168:171], v[208:211], v[4:7]
	v_mfma_f32_16x16x32_bf16 v[0:3], v[176:179], v[208:211], v[0:3]
	v_mfma_f32_16x16x32_bf16 v[52:55], v[172:175], v[188:191], v[52:55]
	v_mfma_f32_16x16x32_bf16 v[48:51], v[180:183], v[188:191], v[48:51]
	v_mfma_f32_16x16x32_bf16 v[36:39], v[172:175], v[196:199], v[36:39]
	v_mfma_f32_16x16x32_bf16 v[32:35], v[180:183], v[196:199], v[32:35]
	s_setprio 2
	s_barrier
	v_mfma_f32_16x16x32_bf16 v[20:23], v[172:175], v[204:207], v[20:23]
	v_mfma_f32_16x16x32_bf16 v[16:19], v[180:183], v[204:207], v[16:19]
	v_mfma_f32_16x16x32_bf16 v[4:7], v[172:175], v[212:215], v[4:7]
	v_mfma_f32_16x16x32_bf16 v[0:3], v[180:183], v[212:215], v[0:3]
	s_setprio 0
	v_lshl_add_u64 v[252:253], s[66:67], 0, v[128:129]
	s_add_i32 m0, s68, 0x2000
	s_nop 0
	global_load_lds_dwordx4 v[252:253], off
	s_add_i32 s66, 0, 0x18000
	s_add_i32 s67, 0, 0x1c000
	v_add_u32_e32 v156, s66, v162
	v_add_u32_e32 v167, s67, v162
	ds_read_b128 v[144:147], v156
	ds_read_b128 v[148:151], v156 offset:1024
	ds_read_b128 v[152:155], v156 offset:2048
	ds_read_b128 v[156:159], v156 offset:3072
	ds_read_b128 v[168:171], v167
	ds_read_b128 v[172:175], v167 offset:1024
	ds_read_b128 v[176:179], v167 offset:2048
	ds_read_b128 v[180:183], v167 offset:3072
	s_add_u32 s40, s40, 0x40000
	s_addc_u32 s41, s41, 0
	s_mov_b32 m0, s54
	v_lshl_add_u64 v[222:223], s[40:41], 0, v[134:135]
	ds_read_b128 v[184:187], v165 offset:32768
	ds_read_b128 v[188:191], v165 offset:33792
	ds_read_b128 v[192:195], v165 offset:34816
	ds_read_b128 v[196:199], v165 offset:35840
	ds_read_b128 v[200:203], v165 offset:36864
	ds_read_b128 v[204:207], v165 offset:37888
	ds_read_b128 v[208:211], v165 offset:38912
	ds_read_b128 v[212:215], v165 offset:39936
	global_load_lds_dwordx4 v[222:223], off
	v_lshl_add_u64 v[222:223], s[40:41], 0, v[130:131]
	s_mov_b32 m0, s55
	s_nop 0
	global_load_lds_dwordx4 v[222:223], off
	s_waitcnt vmcnt(8)
	s_waitcnt lgkmcnt(0)
	s_barrier
	s_setprio 1
	s_waitcnt lgkmcnt(0)
	v_mfma_f32_16x16x32_bf16 v[124:127], v[144:147], v[184:187], v[124:127]
	v_mfma_f32_16x16x32_bf16 v[120:123], v[152:155], v[184:187], v[120:123]
	v_mfma_f32_16x16x32_bf16 v[108:111], v[144:147], v[192:195], v[108:111]
	v_mfma_f32_16x16x32_bf16 v[104:107], v[152:155], v[192:195], v[104:107]
	v_mfma_f32_16x16x32_bf16 v[92:95], v[144:147], v[200:203], v[92:95]
	v_mfma_f32_16x16x32_bf16 v[88:91], v[152:155], v[200:203], v[88:91]
	v_mfma_f32_16x16x32_bf16 v[76:79], v[144:147], v[208:211], v[76:79]
	v_mfma_f32_16x16x32_bf16 v[72:75], v[152:155], v[208:211], v[72:75]
	v_mfma_f32_16x16x32_bf16 v[124:127], v[148:151], v[188:191], v[124:127]
	v_mfma_f32_16x16x32_bf16 v[120:123], v[156:159], v[188:191], v[120:123]
	v_mfma_f32_16x16x32_bf16 v[108:111], v[148:151], v[196:199], v[108:111]
	v_mfma_f32_16x16x32_bf16 v[104:107], v[156:159], v[196:199], v[104:107]
	v_mfma_f32_16x16x32_bf16 v[92:95], v[148:151], v[204:207], v[92:95]
	v_mfma_f32_16x16x32_bf16 v[88:91], v[156:159], v[204:207], v[88:91]
	v_mfma_f32_16x16x32_bf16 v[76:79], v[148:151], v[212:215], v[76:79]
	v_mfma_f32_16x16x32_bf16 v[72:75], v[156:159], v[212:215], v[72:75]
	s_setprio 0
	s_setprio 1
	v_mfma_f32_16x16x32_bf16 v[116:119], v[168:171], v[184:187], v[116:119]
	v_mfma_f32_16x16x32_bf16 v[112:115], v[176:179], v[184:187], v[112:115]
	v_mfma_f32_16x16x32_bf16 v[100:103], v[168:171], v[192:195], v[100:103]
	v_mfma_f32_16x16x32_bf16 v[96:99], v[176:179], v[192:195], v[96:99]
	v_mfma_f32_16x16x32_bf16 v[84:87], v[168:171], v[200:203], v[84:87]
	v_mfma_f32_16x16x32_bf16 v[80:83], v[176:179], v[200:203], v[80:83]
	v_mfma_f32_16x16x32_bf16 v[68:71], v[168:171], v[208:211], v[68:71]
	v_mfma_f32_16x16x32_bf16 v[64:67], v[176:179], v[208:211], v[64:67]
	v_mfma_f32_16x16x32_bf16 v[116:119], v[172:175], v[188:191], v[116:119]
	v_mfma_f32_16x16x32_bf16 v[112:115], v[180:183], v[188:191], v[112:115]
	v_mfma_f32_16x16x32_bf16 v[100:103], v[172:175], v[196:199], v[100:103]
	v_mfma_f32_16x16x32_bf16 v[96:99], v[180:183], v[196:199], v[96:99]
	s_setprio 2
	s_barrier
	v_mfma_f32_16x16x32_bf16 v[84:87], v[172:175], v[204:207], v[84:87]
	v_mfma_f32_16x16x32_bf16 v[80:83], v[180:183], v[204:207], v[80:83]
	v_mfma_f32_16x16x32_bf16 v[68:71], v[172:175], v[212:215], v[68:71]
	v_mfma_f32_16x16x32_bf16 v[64:67], v[180:183], v[212:215], v[64:67]
	s_setprio 0
	s_add_i32 s40, s66, s47
	v_lshl_add_u64 v[160:161], v[160:161], 0, s[16:17]
	s_mov_b32 m0, s40
	ds_read_b128 v[184:187], v165 offset:49152
	ds_read_b128 v[188:191], v165 offset:50176
	ds_read_b128 v[192:195], v165 offset:51200
	ds_read_b128 v[196:199], v165 offset:52224
	ds_read_b128 v[200:203], v165 offset:53248
	ds_read_b128 v[204:207], v165 offset:54272
	ds_read_b128 v[208:211], v165 offset:55296
	ds_read_b128 v[212:215], v165 offset:56320
	global_load_lds_dwordx4 v[160:161], off
	s_add_i32 m0, s40, 0x2000
	s_add_u32 s38, s38, 0x40080
	v_lshl_add_u64 v[160:161], v[216:217], 0, s[16:17]
	s_addc_u32 s39, s39, 0
	s_add_i32 s40, s67, s47
	global_load_lds_dwordx4 v[160:161], off
	v_lshl_add_u64 v[160:161], s[38:39], 0, v[132:133]
	s_mov_b32 m0, s40
	s_nop 0
	global_load_lds_dwordx4 v[160:161], off
	v_lshl_add_u64 v[160:161], s[38:39], 0, v[128:129]
	s_add_i32 m0, s40, 0x2000
	s_nop 0
	global_load_lds_dwordx4 v[160:161], off
	v_lshl_add_u64 v[160:161], v[218:219], 0, s[16:17]
	s_mov_b32 m0, s57
	s_nop 0
	global_load_lds_dwordx4 v[160:161], off
	v_lshl_add_u64 v[160:161], v[220:221], 0, s[16:17]
	s_mov_b32 m0, s58
	s_nop 0
	global_load_lds_dwordx4 v[160:161], off
	s_waitcnt vmcnt(8)
	s_waitcnt lgkmcnt(0)
	s_barrier
	s_setprio 1
	s_waitcnt lgkmcnt(0)
	v_mfma_f32_16x16x32_bf16 v[60:63], v[144:147], v[184:187], v[60:63]
	v_mfma_f32_16x16x32_bf16 v[56:59], v[152:155], v[184:187], v[56:59]
	v_mfma_f32_16x16x32_bf16 v[44:47], v[144:147], v[192:195], v[44:47]
	v_mfma_f32_16x16x32_bf16 v[40:43], v[152:155], v[192:195], v[40:43]
	v_mfma_f32_16x16x32_bf16 v[28:31], v[144:147], v[200:203], v[28:31]
	v_mfma_f32_16x16x32_bf16 v[24:27], v[152:155], v[200:203], v[24:27]
	v_mfma_f32_16x16x32_bf16 v[12:15], v[144:147], v[208:211], v[12:15]
	v_mfma_f32_16x16x32_bf16 v[8:11], v[152:155], v[208:211], v[8:11]
	v_mfma_f32_16x16x32_bf16 v[60:63], v[148:151], v[188:191], v[60:63]
	v_mfma_f32_16x16x32_bf16 v[56:59], v[156:159], v[188:191], v[56:59]
	v_mfma_f32_16x16x32_bf16 v[44:47], v[148:151], v[196:199], v[44:47]
	v_mfma_f32_16x16x32_bf16 v[40:43], v[156:159], v[196:199], v[40:43]
	v_mfma_f32_16x16x32_bf16 v[28:31], v[148:151], v[204:207], v[28:31]
	v_mfma_f32_16x16x32_bf16 v[24:27], v[156:159], v[204:207], v[24:27]
	v_mfma_f32_16x16x32_bf16 v[12:15], v[148:151], v[212:215], v[12:15]
	v_mfma_f32_16x16x32_bf16 v[8:11], v[156:159], v[212:215], v[8:11]
	s_setprio 0
	s_setprio 1
	v_mfma_f32_16x16x32_bf16 v[52:55], v[168:171], v[184:187], v[52:55]
	v_mfma_f32_16x16x32_bf16 v[48:51], v[176:179], v[184:187], v[48:51]
	v_mfma_f32_16x16x32_bf16 v[36:39], v[168:171], v[192:195], v[36:39]
	v_mfma_f32_16x16x32_bf16 v[32:35], v[176:179], v[192:195], v[32:35]
	v_mfma_f32_16x16x32_bf16 v[20:23], v[168:171], v[200:203], v[20:23]
	v_mfma_f32_16x16x32_bf16 v[16:19], v[176:179], v[200:203], v[16:19]
	v_mfma_f32_16x16x32_bf16 v[4:7], v[168:171], v[208:211], v[4:7]
	v_mfma_f32_16x16x32_bf16 v[0:3], v[176:179], v[208:211], v[0:3]
	v_mfma_f32_16x16x32_bf16 v[52:55], v[172:175], v[188:191], v[52:55]
	v_mfma_f32_16x16x32_bf16 v[48:51], v[180:183], v[188:191], v[48:51]
	v_mfma_f32_16x16x32_bf16 v[36:39], v[172:175], v[196:199], v[36:39]
	v_mfma_f32_16x16x32_bf16 v[32:35], v[180:183], v[196:199], v[32:35]
	s_setprio 2
	s_barrier
	v_mfma_f32_16x16x32_bf16 v[20:23], v[172:175], v[204:207], v[20:23]
	v_mfma_f32_16x16x32_bf16 v[16:19], v[180:183], v[204:207], v[16:19]
	v_mfma_f32_16x16x32_bf16 v[4:7], v[172:175], v[212:215], v[4:7]
	v_mfma_f32_16x16x32_bf16 v[0:3], v[180:183], v[212:215], v[0:3]
	s_setprio 0
	s_add_i32 s65, s65, 2
	s_add_u32 s36, s36, 0x100
	s_addc_u32 s37, s37, 0
	s_add_u32 s63, s63, 0x100
	s_addc_u32 s64, s64, 0
	s_cmp_gt_u32 s65, 13
	s_cbranch_scc0 .LBB0_784

.LBB0_866:
	ds_read_b128 v[120:123], v233
	ds_read_b128 v[124:127], v233 offset:1024
	ds_read_b128 v[136:139], v233 offset:2048
	ds_read_b128 v[140:143], v233 offset:3072
	ds_read_b128 v[144:147], v234
	ds_read_b128 v[148:151], v234 offset:1024
	ds_read_b128 v[152:155], v234 offset:2048
	ds_read_b128 v[156:159], v234 offset:3072
	s_add_u32 s28, s26, 0x100
	s_addc_u32 s29, s27, 0
	s_cmp_eq_u32 s64, 40
	s_cselect_b32 s37, s7, s29
	s_cselect_b32 s36, s6, s28
	s_cselect_b32 s31, s25, s63
	s_cselect_b32 s30, s24, s62
	v_lshl_add_u64 v[208:209], s[26:27], 0, v[192:193]
	s_add_i32 m0, s44, 0xc000
	ds_read_b128 v[160:163], v235
	ds_read_b128 v[164:167], v235 offset:1024
	ds_read_b128 v[168:171], v235 offset:2048
	ds_read_b128 v[172:175], v235 offset:3072
	ds_read_b128 v[176:179], v235 offset:4096
	ds_read_b128 v[180:183], v235 offset:5120
	ds_read_b128 v[200:203], v235 offset:6144
	ds_read_b128 v[204:207], v235 offset:7168
	global_load_lds_dwordx4 v[208:209], off
	v_lshl_add_u64 v[208:209], s[26:27], 0, v[194:195]
	s_add_i32 m0, s44, 0xe000
	s_nop 0
	global_load_lds_dwordx4 v[208:209], off
	s_waitcnt vmcnt(8)
	s_waitcnt lgkmcnt(0)
	s_barrier
	s_setprio 1
	s_waitcnt lgkmcnt(0)
	v_mfma_f32_16x16x32_bf16 v[132:135], v[120:123], v[160:163], v[132:135]
	v_mfma_f32_16x16x32_bf16 v[128:131], v[136:139], v[160:163], v[128:131]
	v_mfma_f32_16x16x32_bf16 v[108:111], v[120:123], v[168:171], v[108:111]
	v_mfma_f32_16x16x32_bf16 v[104:107], v[136:139], v[168:171], v[104:107]
	v_mfma_f32_16x16x32_bf16 v[92:95], v[120:123], v[176:179], v[92:95]
	v_mfma_f32_16x16x32_bf16 v[88:91], v[136:139], v[176:179], v[88:91]
	v_mfma_f32_16x16x32_bf16 v[76:79], v[120:123], v[200:203], v[76:79]
	v_mfma_f32_16x16x32_bf16 v[72:75], v[136:139], v[200:203], v[72:75]
	v_mfma_f32_16x16x32_bf16 v[132:135], v[124:127], v[164:167], v[132:135]
	v_mfma_f32_16x16x32_bf16 v[128:131], v[140:143], v[164:167], v[128:131]
	v_mfma_f32_16x16x32_bf16 v[108:111], v[124:127], v[172:175], v[108:111]
	v_mfma_f32_16x16x32_bf16 v[104:107], v[140:143], v[172:175], v[104:107]
	v_mfma_f32_16x16x32_bf16 v[92:95], v[124:127], v[180:183], v[92:95]
	v_mfma_f32_16x16x32_bf16 v[88:91], v[140:143], v[180:183], v[88:91]
	v_mfma_f32_16x16x32_bf16 v[76:79], v[124:127], v[204:207], v[76:79]
	v_mfma_f32_16x16x32_bf16 v[72:75], v[140:143], v[204:207], v[72:75]
	s_setprio 0
	s_setprio 1
	v_mfma_f32_16x16x32_bf16 v[116:119], v[144:147], v[160:163], v[116:119]
	v_mfma_f32_16x16x32_bf16 v[112:115], v[152:155], v[160:163], v[112:115]
	v_mfma_f32_16x16x32_bf16 v[100:103], v[144:147], v[168:171], v[100:103]
	v_mfma_f32_16x16x32_bf16 v[96:99], v[152:155], v[168:171], v[96:99]
	v_mfma_f32_16x16x32_bf16 v[84:87], v[144:147], v[176:179], v[84:87]
	v_mfma_f32_16x16x32_bf16 v[80:83], v[152:155], v[176:179], v[80:83]
	v_mfma_f32_16x16x32_bf16 v[68:71], v[144:147], v[200:203], v[68:71]
	v_mfma_f32_16x16x32_bf16 v[64:67], v[152:155], v[200:203], v[64:67]
	v_mfma_f32_16x16x32_bf16 v[116:119], v[148:151], v[164:167], v[116:119]
	v_mfma_f32_16x16x32_bf16 v[112:115], v[156:159], v[164:167], v[112:115]
	v_mfma_f32_16x16x32_bf16 v[100:103], v[148:151], v[172:175], v[100:103]
	v_mfma_f32_16x16x32_bf16 v[96:99], v[156:159], v[172:175], v[96:99]
	s_setprio 2
	s_barrier
	v_mfma_f32_16x16x32_bf16 v[84:87], v[148:151], v[180:183], v[84:87]
	v_mfma_f32_16x16x32_bf16 v[80:83], v[156:159], v[180:183], v[80:83]
	v_mfma_f32_16x16x32_bf16 v[68:71], v[148:151], v[204:207], v[68:71]
	v_mfma_f32_16x16x32_bf16 v[64:67], v[156:159], v[204:207], v[64:67]
	s_setprio 0
	s_add_i32 s26, s56, s43
	v_lshl_add_u64 v[208:209], s[30:31], 0, v[186:187]
	s_mov_b32 m0, s26
	ds_read_b128 v[160:163], v235 offset:16384
	ds_read_b128 v[164:167], v235 offset:17408
	ds_read_b128 v[168:171], v235 offset:18432
	ds_read_b128 v[172:175], v235 offset:19456
	ds_read_b128 v[176:179], v235 offset:20480
	ds_read_b128 v[180:183], v235 offset:21504
	ds_read_b128 v[200:203], v235 offset:22528
	ds_read_b128 v[204:207], v235 offset:23552
	global_load_lds_dwordx4 v[208:209], off
	s_add_i32 m0, s26, 0x2000
	s_add_u32 s26, s30, 0xb0000
	v_lshl_add_u64 v[210:211], s[30:31], 0, v[190:191]
	s_addc_u32 s27, s31, 0
	s_add_i32 s65, s57, s43
	global_load_lds_dwordx4 v[210:211], off
	v_lshl_add_u64 v[212:213], s[26:27], 0, v[186:187]
	s_mov_b32 m0, s65
	v_lshl_add_u64 v[214:215], s[36:37], 0, v[188:189]
	global_load_lds_dwordx4 v[212:213], off
	v_lshl_add_u64 v[212:213], s[36:37], 0, v[184:185]
	s_mov_b32 m0, s44
	s_nop 0
	global_load_lds_dwordx4 v[212:213], off
	s_mov_b32 m0, s45
	s_nop 0
	global_load_lds_dwordx4 v[214:215], off
	s_waitcnt vmcnt(7)
	s_waitcnt lgkmcnt(0)
	s_barrier
	s_setprio 1
	s_waitcnt lgkmcnt(0)
	v_mfma_f32_16x16x32_bf16 v[60:63], v[120:123], v[160:163], v[60:63]
	v_mfma_f32_16x16x32_bf16 v[56:59], v[136:139], v[160:163], v[56:59]
	v_mfma_f32_16x16x32_bf16 v[44:47], v[120:123], v[168:171], v[44:47]
	v_mfma_f32_16x16x32_bf16 v[40:43], v[136:139], v[168:171], v[40:43]
	v_mfma_f32_16x16x32_bf16 v[28:31], v[120:123], v[176:179], v[28:31]
	v_mfma_f32_16x16x32_bf16 v[24:27], v[136:139], v[176:179], v[24:27]
	v_mfma_f32_16x16x32_bf16 v[12:15], v[120:123], v[200:203], v[12:15]
	v_mfma_f32_16x16x32_bf16 v[8:11], v[136:139], v[200:203], v[8:11]
	v_mfma_f32_16x16x32_bf16 v[60:63], v[124:127], v[164:167], v[60:63]
	v_mfma_f32_16x16x32_bf16 v[56:59], v[140:143], v[164:167], v[56:59]
	v_mfma_f32_16x16x32_bf16 v[44:47], v[124:127], v[172:175], v[44:47]
	v_mfma_f32_16x16x32_bf16 v[40:43], v[140:143], v[172:175], v[40:43]
	v_mfma_f32_16x16x32_bf16 v[28:31], v[124:127], v[180:183], v[28:31]
	v_mfma_f32_16x16x32_bf16 v[24:27], v[140:143], v[180:183], v[24:27]
	v_mfma_f32_16x16x32_bf16 v[12:15], v[124:127], v[204:207], v[12:15]
	v_mfma_f32_16x16x32_bf16 v[8:11], v[140:143], v[204:207], v[8:11]
	s_setprio 0
	s_setprio 1
	v_mfma_f32_16x16x32_bf16 v[52:55], v[144:147], v[160:163], v[52:55]
	v_mfma_f32_16x16x32_bf16 v[48:51], v[152:155], v[160:163], v[48:51]
	v_mfma_f32_16x16x32_bf16 v[36:39], v[144:147], v[168:171], v[36:39]
	v_mfma_f32_16x16x32_bf16 v[32:35], v[152:155], v[168:171], v[32:35]
	v_mfma_f32_16x16x32_bf16 v[20:23], v[144:147], v[176:179], v[20:23]
	v_mfma_f32_16x16x32_bf16 v[16:19], v[152:155], v[176:179], v[16:19]
	v_mfma_f32_16x16x32_bf16 v[4:7], v[144:147], v[200:203], v[4:7]
	v_mfma_f32_16x16x32_bf16 v[0:3], v[152:155], v[200:203], v[0:3]
	v_mfma_f32_16x16x32_bf16 v[52:55], v[148:151], v[164:167], v[52:55]
	v_mfma_f32_16x16x32_bf16 v[48:51], v[156:159], v[164:167], v[48:51]
	v_mfma_f32_16x16x32_bf16 v[36:39], v[148:151], v[172:175], v[36:39]
	v_mfma_f32_16x16x32_bf16 v[32:35], v[156:159], v[172:175], v[32:35]
	s_setprio 2
	s_barrier
	v_mfma_f32_16x16x32_bf16 v[20:23], v[148:151], v[180:183], v[20:23]
	v_mfma_f32_16x16x32_bf16 v[16:19], v[156:159], v[180:183], v[16:19]
	v_mfma_f32_16x16x32_bf16 v[4:7], v[148:151], v[204:207], v[4:7]
	v_mfma_f32_16x16x32_bf16 v[0:3], v[156:159], v[204:207], v[0:3]
	s_setprio 0
	v_lshl_add_u64 v[252:253], s[26:27], 0, v[190:191]
	s_add_i32 m0, s65, 0x2000
	s_nop 0
	global_load_lds_dwordx4 v[252:253], off
	s_add_i32 s65, 0, 0x18000
	s_add_i32 s66, 0, 0x1c000
	v_add_u32_e32 v140, s65, v232
	v_add_u32_e32 v156, s66, v232
	ds_read_b128 v[120:123], v140
	ds_read_b128 v[124:127], v140 offset:1024
	ds_read_b128 v[136:139], v140 offset:2048
	ds_read_b128 v[140:143], v140 offset:3072
	ds_read_b128 v[144:147], v156
	ds_read_b128 v[148:151], v156 offset:1024
	ds_read_b128 v[152:155], v156 offset:2048
	ds_read_b128 v[156:159], v156 offset:3072
	s_add_u32 s26, s36, 0xb0000
	s_addc_u32 s27, s37, 0
	s_mov_b32 m0, s46
	v_lshl_add_u64 v[216:217], s[26:27], 0, v[184:185]
	ds_read_b128 v[160:163], v235 offset:32768
	ds_read_b128 v[164:167], v235 offset:33792
	ds_read_b128 v[168:171], v235 offset:34816
	ds_read_b128 v[172:175], v235 offset:35840
	ds_read_b128 v[176:179], v235 offset:36864
	ds_read_b128 v[180:183], v235 offset:37888
	ds_read_b128 v[200:203], v235 offset:38912
	ds_read_b128 v[204:207], v235 offset:39936
	global_load_lds_dwordx4 v[216:217], off
	v_lshl_add_u64 v[216:217], s[26:27], 0, v[188:189]
	s_mov_b32 m0, s47
	s_nop 0
	global_load_lds_dwordx4 v[216:217], off
	s_waitcnt vmcnt(8)
	s_waitcnt lgkmcnt(0)
	s_barrier
	s_setprio 1
	s_waitcnt lgkmcnt(0)
	v_mfma_f32_16x16x32_bf16 v[132:135], v[120:123], v[160:163], v[132:135]
	v_mfma_f32_16x16x32_bf16 v[128:131], v[136:139], v[160:163], v[128:131]
	v_mfma_f32_16x16x32_bf16 v[108:111], v[120:123], v[168:171], v[108:111]
	v_mfma_f32_16x16x32_bf16 v[104:107], v[136:139], v[168:171], v[104:107]
	v_mfma_f32_16x16x32_bf16 v[92:95], v[120:123], v[176:179], v[92:95]
	v_mfma_f32_16x16x32_bf16 v[88:91], v[136:139], v[176:179], v[88:91]
	v_mfma_f32_16x16x32_bf16 v[76:79], v[120:123], v[200:203], v[76:79]
	v_mfma_f32_16x16x32_bf16 v[72:75], v[136:139], v[200:203], v[72:75]
	v_mfma_f32_16x16x32_bf16 v[132:135], v[124:127], v[164:167], v[132:135]
	v_mfma_f32_16x16x32_bf16 v[128:131], v[140:143], v[164:167], v[128:131]
	v_mfma_f32_16x16x32_bf16 v[108:111], v[124:127], v[172:175], v[108:111]
	v_mfma_f32_16x16x32_bf16 v[104:107], v[140:143], v[172:175], v[104:107]
	v_mfma_f32_16x16x32_bf16 v[92:95], v[124:127], v[180:183], v[92:95]
	v_mfma_f32_16x16x32_bf16 v[88:91], v[140:143], v[180:183], v[88:91]
	v_mfma_f32_16x16x32_bf16 v[76:79], v[124:127], v[204:207], v[76:79]
	v_mfma_f32_16x16x32_bf16 v[72:75], v[140:143], v[204:207], v[72:75]
	s_setprio 0
	s_setprio 1
	v_mfma_f32_16x16x32_bf16 v[116:119], v[144:147], v[160:163], v[116:119]
	v_mfma_f32_16x16x32_bf16 v[112:115], v[152:155], v[160:163], v[112:115]
	v_mfma_f32_16x16x32_bf16 v[100:103], v[144:147], v[168:171], v[100:103]
	v_mfma_f32_16x16x32_bf16 v[96:99], v[152:155], v[168:171], v[96:99]
	v_mfma_f32_16x16x32_bf16 v[84:87], v[144:147], v[176:179], v[84:87]
	v_mfma_f32_16x16x32_bf16 v[80:83], v[152:155], v[176:179], v[80:83]
	v_mfma_f32_16x16x32_bf16 v[68:71], v[144:147], v[200:203], v[68:71]
	v_mfma_f32_16x16x32_bf16 v[64:67], v[152:155], v[200:203], v[64:67]
	v_mfma_f32_16x16x32_bf16 v[116:119], v[148:151], v[164:167], v[116:119]
	v_mfma_f32_16x16x32_bf16 v[112:115], v[156:159], v[164:167], v[112:115]
	v_mfma_f32_16x16x32_bf16 v[100:103], v[148:151], v[172:175], v[100:103]
	v_mfma_f32_16x16x32_bf16 v[96:99], v[156:159], v[172:175], v[96:99]
	s_setprio 2
	s_barrier
	v_mfma_f32_16x16x32_bf16 v[84:87], v[148:151], v[180:183], v[84:87]
	v_mfma_f32_16x16x32_bf16 v[80:83], v[156:159], v[180:183], v[80:83]
	v_mfma_f32_16x16x32_bf16 v[68:71], v[148:151], v[204:207], v[68:71]
	v_mfma_f32_16x16x32_bf16 v[64:67], v[156:159], v[204:207], v[64:67]
	s_setprio 0
	s_add_i32 s26, s65, s43
	v_lshl_add_u64 v[208:209], v[208:209], 0, s[20:21]
	s_mov_b32 m0, s26
	ds_read_b128 v[160:163], v235 offset:49152
	ds_read_b128 v[164:167], v235 offset:50176
	ds_read_b128 v[168:171], v235 offset:51200
	ds_read_b128 v[172:175], v235 offset:52224
	ds_read_b128 v[176:179], v235 offset:53248
	ds_read_b128 v[180:183], v235 offset:54272
	ds_read_b128 v[200:203], v235 offset:55296
	ds_read_b128 v[204:207], v235 offset:56320
	global_load_lds_dwordx4 v[208:209], off
	s_add_i32 m0, s26, 0x2000
	s_add_u32 s26, s30, 0xb0080
	v_lshl_add_u64 v[208:209], v[210:211], 0, s[20:21]
	s_addc_u32 s27, s31, 0
	s_add_i32 s30, s66, s43
	global_load_lds_dwordx4 v[208:209], off
	v_lshl_add_u64 v[208:209], s[26:27], 0, v[186:187]
	s_mov_b32 m0, s30
	s_nop 0
	global_load_lds_dwordx4 v[208:209], off
	v_lshl_add_u64 v[208:209], s[26:27], 0, v[190:191]
	s_add_i32 m0, s30, 0x2000
	s_nop 0
	global_load_lds_dwordx4 v[208:209], off
	v_lshl_add_u64 v[208:209], v[212:213], 0, s[20:21]
	s_mov_b32 m0, s49
	s_nop 0
	global_load_lds_dwordx4 v[208:209], off
	v_lshl_add_u64 v[208:209], v[214:215], 0, s[20:21]
	s_mov_b32 m0, s50
	s_nop 0
	global_load_lds_dwordx4 v[208:209], off
	s_waitcnt vmcnt(8)
	s_waitcnt lgkmcnt(0)
	s_barrier
	s_setprio 1
	s_waitcnt lgkmcnt(0)
	v_mfma_f32_16x16x32_bf16 v[60:63], v[120:123], v[160:163], v[60:63]
	v_mfma_f32_16x16x32_bf16 v[56:59], v[136:139], v[160:163], v[56:59]
	v_mfma_f32_16x16x32_bf16 v[44:47], v[120:123], v[168:171], v[44:47]
	v_mfma_f32_16x16x32_bf16 v[40:43], v[136:139], v[168:171], v[40:43]
	v_mfma_f32_16x16x32_bf16 v[28:31], v[120:123], v[176:179], v[28:31]
	v_mfma_f32_16x16x32_bf16 v[24:27], v[136:139], v[176:179], v[24:27]
	v_mfma_f32_16x16x32_bf16 v[12:15], v[120:123], v[200:203], v[12:15]
	v_mfma_f32_16x16x32_bf16 v[8:11], v[136:139], v[200:203], v[8:11]
	v_mfma_f32_16x16x32_bf16 v[60:63], v[124:127], v[164:167], v[60:63]
	v_mfma_f32_16x16x32_bf16 v[56:59], v[140:143], v[164:167], v[56:59]
	v_mfma_f32_16x16x32_bf16 v[44:47], v[124:127], v[172:175], v[44:47]
	v_mfma_f32_16x16x32_bf16 v[40:43], v[140:143], v[172:175], v[40:43]
	v_mfma_f32_16x16x32_bf16 v[28:31], v[124:127], v[180:183], v[28:31]
	v_mfma_f32_16x16x32_bf16 v[24:27], v[140:143], v[180:183], v[24:27]
	v_mfma_f32_16x16x32_bf16 v[12:15], v[124:127], v[204:207], v[12:15]
	v_mfma_f32_16x16x32_bf16 v[8:11], v[140:143], v[204:207], v[8:11]
	s_setprio 0
	s_setprio 1
	v_mfma_f32_16x16x32_bf16 v[52:55], v[144:147], v[160:163], v[52:55]
	v_mfma_f32_16x16x32_bf16 v[48:51], v[152:155], v[160:163], v[48:51]
	v_mfma_f32_16x16x32_bf16 v[36:39], v[144:147], v[168:171], v[36:39]
	v_mfma_f32_16x16x32_bf16 v[32:35], v[152:155], v[168:171], v[32:35]
	v_mfma_f32_16x16x32_bf16 v[20:23], v[144:147], v[176:179], v[20:23]
	v_mfma_f32_16x16x32_bf16 v[16:19], v[152:155], v[176:179], v[16:19]
	v_mfma_f32_16x16x32_bf16 v[4:7], v[144:147], v[200:203], v[4:7]
	v_mfma_f32_16x16x32_bf16 v[0:3], v[152:155], v[200:203], v[0:3]
	v_mfma_f32_16x16x32_bf16 v[52:55], v[148:151], v[164:167], v[52:55]
	v_mfma_f32_16x16x32_bf16 v[48:51], v[156:159], v[164:167], v[48:51]
	v_mfma_f32_16x16x32_bf16 v[36:39], v[148:151], v[172:175], v[36:39]
	v_mfma_f32_16x16x32_bf16 v[32:35], v[156:159], v[172:175], v[32:35]
	s_setprio 2
	s_barrier
	v_mfma_f32_16x16x32_bf16 v[20:23], v[148:151], v[180:183], v[20:23]
	v_mfma_f32_16x16x32_bf16 v[16:19], v[156:159], v[180:183], v[16:19]
	v_mfma_f32_16x16x32_bf16 v[4:7], v[148:151], v[204:207], v[4:7]
	v_mfma_f32_16x16x32_bf16 v[0:3], v[156:159], v[204:207], v[0:3]
	s_setprio 0
	s_add_i32 s64, s64, 2
	s_add_u32 s62, s62, 0x100
	s_addc_u32 s63, s63, 0
	s_cmp_gt_u32 s64, 41
	s_mov_b64 s[26:27], s[28:29]
	s_cbranch_scc0 .LBB0_866

.LBB0_952:
	ds_read_b128 v[144:147], v179
	ds_read_b128 v[148:151], v179 offset:1024
	ds_read_b128 v[152:155], v179 offset:2048
	ds_read_b128 v[156:159], v179 offset:3072
	ds_read_b128 v[160:163], v180
	ds_read_b128 v[164:167], v180 offset:1024
	ds_read_b128 v[168:171], v180 offset:2048
	ds_read_b128 v[172:175], v180 offset:3072
	s_add_u32 s40, s6, 0xfffc0080
	s_addc_u32 s41, s7, -1
	s_cmp_eq_u32 s73, 12
	s_cselect_b32 s45, s27, s41
	s_cselect_b32 s44, s39, s40
	s_cselect_b32 s41, s29, s72
	s_cselect_b32 s40, s43, s71
	v_lshl_add_u64 v[176:177], s[6:7], 0, v[136:137]
	s_add_i32 m0, s54, 0xc000
	ds_read_b128 v[184:187], v181
	ds_read_b128 v[188:191], v181 offset:1024
	ds_read_b128 v[192:195], v181 offset:2048
	ds_read_b128 v[196:199], v181 offset:3072
	ds_read_b128 v[200:203], v181 offset:4096
	ds_read_b128 v[204:207], v181 offset:5120
	ds_read_b128 v[208:211], v181 offset:6144
	ds_read_b128 v[212:215], v181 offset:7168
	global_load_lds_dwordx4 v[176:177], off
	v_lshl_add_u64 v[176:177], s[6:7], 0, v[138:139]
	s_add_i32 m0, s54, 0xe000
	s_nop 0
	global_load_lds_dwordx4 v[176:177], off
	s_waitcnt vmcnt(8)
	s_waitcnt lgkmcnt(0)
	s_barrier
	s_setprio 1
	s_waitcnt lgkmcnt(0)
	v_mfma_f32_16x16x32_bf16 v[124:127], v[144:147], v[184:187], v[124:127]
	v_mfma_f32_16x16x32_bf16 v[120:123], v[152:155], v[184:187], v[120:123]
	v_mfma_f32_16x16x32_bf16 v[108:111], v[144:147], v[192:195], v[108:111]
	v_mfma_f32_16x16x32_bf16 v[104:107], v[152:155], v[192:195], v[104:107]
	v_mfma_f32_16x16x32_bf16 v[92:95], v[144:147], v[200:203], v[92:95]
	v_mfma_f32_16x16x32_bf16 v[88:91], v[152:155], v[200:203], v[88:91]
	v_mfma_f32_16x16x32_bf16 v[76:79], v[144:147], v[208:211], v[76:79]
	v_mfma_f32_16x16x32_bf16 v[72:75], v[152:155], v[208:211], v[72:75]
	v_mfma_f32_16x16x32_bf16 v[124:127], v[148:151], v[188:191], v[124:127]
	v_mfma_f32_16x16x32_bf16 v[120:123], v[156:159], v[188:191], v[120:123]
	v_mfma_f32_16x16x32_bf16 v[108:111], v[148:151], v[196:199], v[108:111]
	v_mfma_f32_16x16x32_bf16 v[104:107], v[156:159], v[196:199], v[104:107]
	v_mfma_f32_16x16x32_bf16 v[92:95], v[148:151], v[204:207], v[92:95]
	v_mfma_f32_16x16x32_bf16 v[88:91], v[156:159], v[204:207], v[88:91]
	v_mfma_f32_16x16x32_bf16 v[76:79], v[148:151], v[212:215], v[76:79]
	v_mfma_f32_16x16x32_bf16 v[72:75], v[156:159], v[212:215], v[72:75]
	s_setprio 0
	s_setprio 1
	v_mfma_f32_16x16x32_bf16 v[116:119], v[160:163], v[184:187], v[116:119]
	v_mfma_f32_16x16x32_bf16 v[112:115], v[168:171], v[184:187], v[112:115]
	v_mfma_f32_16x16x32_bf16 v[100:103], v[160:163], v[192:195], v[100:103]
	v_mfma_f32_16x16x32_bf16 v[96:99], v[168:171], v[192:195], v[96:99]
	v_mfma_f32_16x16x32_bf16 v[84:87], v[160:163], v[200:203], v[84:87]
	v_mfma_f32_16x16x32_bf16 v[80:83], v[168:171], v[200:203], v[80:83]
	v_mfma_f32_16x16x32_bf16 v[68:71], v[160:163], v[208:211], v[68:71]
	v_mfma_f32_16x16x32_bf16 v[64:67], v[168:171], v[208:211], v[64:67]
	v_mfma_f32_16x16x32_bf16 v[116:119], v[164:167], v[188:191], v[116:119]
	v_mfma_f32_16x16x32_bf16 v[112:115], v[172:175], v[188:191], v[112:115]
	v_mfma_f32_16x16x32_bf16 v[100:103], v[164:167], v[196:199], v[100:103]
	v_mfma_f32_16x16x32_bf16 v[96:99], v[172:175], v[196:199], v[96:99]
	s_setprio 2
	s_barrier
	v_mfma_f32_16x16x32_bf16 v[84:87], v[164:167], v[204:207], v[84:87]
	v_mfma_f32_16x16x32_bf16 v[80:83], v[172:175], v[204:207], v[80:83]
	v_mfma_f32_16x16x32_bf16 v[68:71], v[164:167], v[212:215], v[68:71]
	v_mfma_f32_16x16x32_bf16 v[64:67], v[172:175], v[212:215], v[64:67]
	s_setprio 0
	s_add_i32 s74, s69, s51
	v_lshl_add_u64 v[176:177], s[40:41], 0, v[130:131]
	s_mov_b32 m0, s74
	ds_read_b128 v[184:187], v181 offset:16384
	ds_read_b128 v[188:191], v181 offset:17408
	ds_read_b128 v[192:195], v181 offset:18432
	ds_read_b128 v[196:199], v181 offset:19456
	ds_read_b128 v[200:203], v181 offset:20480
	ds_read_b128 v[204:207], v181 offset:21504
	ds_read_b128 v[208:211], v181 offset:22528
	ds_read_b128 v[212:215], v181 offset:23552
	global_load_lds_dwordx4 v[176:177], off
	s_add_i32 m0, s74, 0x2000
	s_add_u32 s74, s40, 0x40000
	v_lshl_add_u64 v[216:217], s[40:41], 0, v[134:135]
	s_addc_u32 s75, s41, 0
	s_add_i32 s76, s70, s51
	global_load_lds_dwordx4 v[216:217], off
	v_lshl_add_u64 v[218:219], s[74:75], 0, v[130:131]
	s_mov_b32 m0, s76
	v_lshl_add_u64 v[220:221], s[44:45], 0, v[132:133]
	global_load_lds_dwordx4 v[218:219], off
	v_lshl_add_u64 v[218:219], s[44:45], 0, v[128:129]
	s_mov_b32 m0, s54
	s_nop 0
	global_load_lds_dwordx4 v[218:219], off
	s_mov_b32 m0, s55
	s_nop 0
	global_load_lds_dwordx4 v[220:221], off
	s_waitcnt vmcnt(7)
	s_waitcnt lgkmcnt(0)
	s_barrier
	s_setprio 1
	s_waitcnt lgkmcnt(0)
	v_mfma_f32_16x16x32_bf16 v[60:63], v[144:147], v[184:187], v[60:63]
	v_mfma_f32_16x16x32_bf16 v[56:59], v[152:155], v[184:187], v[56:59]
	v_mfma_f32_16x16x32_bf16 v[44:47], v[144:147], v[192:195], v[44:47]
	v_mfma_f32_16x16x32_bf16 v[40:43], v[152:155], v[192:195], v[40:43]
	v_mfma_f32_16x16x32_bf16 v[28:31], v[144:147], v[200:203], v[28:31]
	v_mfma_f32_16x16x32_bf16 v[24:27], v[152:155], v[200:203], v[24:27]
	v_mfma_f32_16x16x32_bf16 v[12:15], v[144:147], v[208:211], v[12:15]
	v_mfma_f32_16x16x32_bf16 v[8:11], v[152:155], v[208:211], v[8:11]
	v_mfma_f32_16x16x32_bf16 v[60:63], v[148:151], v[188:191], v[60:63]
	v_mfma_f32_16x16x32_bf16 v[56:59], v[156:159], v[188:191], v[56:59]
	v_mfma_f32_16x16x32_bf16 v[44:47], v[148:151], v[196:199], v[44:47]
	v_mfma_f32_16x16x32_bf16 v[40:43], v[156:159], v[196:199], v[40:43]
	v_mfma_f32_16x16x32_bf16 v[28:31], v[148:151], v[204:207], v[28:31]
	v_mfma_f32_16x16x32_bf16 v[24:27], v[156:159], v[204:207], v[24:27]
	v_mfma_f32_16x16x32_bf16 v[12:15], v[148:151], v[212:215], v[12:15]
	v_mfma_f32_16x16x32_bf16 v[8:11], v[156:159], v[212:215], v[8:11]
	s_setprio 0
	s_setprio 1
	v_mfma_f32_16x16x32_bf16 v[52:55], v[160:163], v[184:187], v[52:55]
	v_mfma_f32_16x16x32_bf16 v[48:51], v[168:171], v[184:187], v[48:51]
	v_mfma_f32_16x16x32_bf16 v[36:39], v[160:163], v[192:195], v[36:39]
	v_mfma_f32_16x16x32_bf16 v[32:35], v[168:171], v[192:195], v[32:35]
	v_mfma_f32_16x16x32_bf16 v[20:23], v[160:163], v[200:203], v[20:23]
	v_mfma_f32_16x16x32_bf16 v[16:19], v[168:171], v[200:203], v[16:19]
	v_mfma_f32_16x16x32_bf16 v[4:7], v[160:163], v[208:211], v[4:7]
	v_mfma_f32_16x16x32_bf16 v[0:3], v[168:171], v[208:211], v[0:3]
	v_mfma_f32_16x16x32_bf16 v[52:55], v[164:167], v[188:191], v[52:55]
	v_mfma_f32_16x16x32_bf16 v[48:51], v[172:175], v[188:191], v[48:51]
	v_mfma_f32_16x16x32_bf16 v[36:39], v[164:167], v[196:199], v[36:39]
	v_mfma_f32_16x16x32_bf16 v[32:35], v[172:175], v[196:199], v[32:35]
	s_setprio 2
	s_barrier
	v_mfma_f32_16x16x32_bf16 v[20:23], v[164:167], v[204:207], v[20:23]
	v_mfma_f32_16x16x32_bf16 v[16:19], v[172:175], v[204:207], v[16:19]
	v_mfma_f32_16x16x32_bf16 v[4:7], v[164:167], v[212:215], v[4:7]
	v_mfma_f32_16x16x32_bf16 v[0:3], v[172:175], v[212:215], v[0:3]
	s_setprio 0
	v_lshl_add_u64 v[252:253], s[74:75], 0, v[134:135]
	s_add_i32 m0, s76, 0x2000
	s_nop 0
	global_load_lds_dwordx4 v[252:253], off
	s_add_i32 s74, 0, 0x18000
	s_add_i32 s75, 0, 0x1c000
	v_add_u32_e32 v156, s74, v178
	v_add_u32_e32 v172, s75, v178
	ds_read_b128 v[144:147], v156
	ds_read_b128 v[148:151], v156 offset:1024
	ds_read_b128 v[152:155], v156 offset:2048
	ds_read_b128 v[156:159], v156 offset:3072
	ds_read_b128 v[160:163], v172
	ds_read_b128 v[164:167], v172 offset:1024
	ds_read_b128 v[168:171], v172 offset:2048
	ds_read_b128 v[172:175], v172 offset:3072
	s_add_u32 s44, s44, 0x40000
	s_addc_u32 s45, s45, 0
	s_mov_b32 m0, s56
	v_lshl_add_u64 v[222:223], s[44:45], 0, v[128:129]
	ds_read_b128 v[184:187], v181 offset:32768
	ds_read_b128 v[188:191], v181 offset:33792
	ds_read_b128 v[192:195], v181 offset:34816
	ds_read_b128 v[196:199], v181 offset:35840
	ds_read_b128 v[200:203], v181 offset:36864
	ds_read_b128 v[204:207], v181 offset:37888
	ds_read_b128 v[208:211], v181 offset:38912
	ds_read_b128 v[212:215], v181 offset:39936
	global_load_lds_dwordx4 v[222:223], off
	v_lshl_add_u64 v[222:223], s[44:45], 0, v[132:133]
	s_mov_b32 m0, s57
	s_nop 0
	global_load_lds_dwordx4 v[222:223], off
	s_waitcnt vmcnt(8)
	s_waitcnt lgkmcnt(0)
	s_barrier
	s_setprio 1
	s_waitcnt lgkmcnt(0)
	v_mfma_f32_16x16x32_bf16 v[124:127], v[144:147], v[184:187], v[124:127]
	v_mfma_f32_16x16x32_bf16 v[120:123], v[152:155], v[184:187], v[120:123]
	v_mfma_f32_16x16x32_bf16 v[108:111], v[144:147], v[192:195], v[108:111]
	v_mfma_f32_16x16x32_bf16 v[104:107], v[152:155], v[192:195], v[104:107]
	v_mfma_f32_16x16x32_bf16 v[92:95], v[144:147], v[200:203], v[92:95]
	v_mfma_f32_16x16x32_bf16 v[88:91], v[152:155], v[200:203], v[88:91]
	v_mfma_f32_16x16x32_bf16 v[76:79], v[144:147], v[208:211], v[76:79]
	v_mfma_f32_16x16x32_bf16 v[72:75], v[152:155], v[208:211], v[72:75]
	v_mfma_f32_16x16x32_bf16 v[124:127], v[148:151], v[188:191], v[124:127]
	v_mfma_f32_16x16x32_bf16 v[120:123], v[156:159], v[188:191], v[120:123]
	v_mfma_f32_16x16x32_bf16 v[108:111], v[148:151], v[196:199], v[108:111]
	v_mfma_f32_16x16x32_bf16 v[104:107], v[156:159], v[196:199], v[104:107]
	v_mfma_f32_16x16x32_bf16 v[92:95], v[148:151], v[204:207], v[92:95]
	v_mfma_f32_16x16x32_bf16 v[88:91], v[156:159], v[204:207], v[88:91]
	v_mfma_f32_16x16x32_bf16 v[76:79], v[148:151], v[212:215], v[76:79]
	v_mfma_f32_16x16x32_bf16 v[72:75], v[156:159], v[212:215], v[72:75]
	s_setprio 0
	s_setprio 1
	v_mfma_f32_16x16x32_bf16 v[116:119], v[160:163], v[184:187], v[116:119]
	v_mfma_f32_16x16x32_bf16 v[112:115], v[168:171], v[184:187], v[112:115]
	v_mfma_f32_16x16x32_bf16 v[100:103], v[160:163], v[192:195], v[100:103]
	v_mfma_f32_16x16x32_bf16 v[96:99], v[168:171], v[192:195], v[96:99]
	v_mfma_f32_16x16x32_bf16 v[84:87], v[160:163], v[200:203], v[84:87]
	v_mfma_f32_16x16x32_bf16 v[80:83], v[168:171], v[200:203], v[80:83]
	v_mfma_f32_16x16x32_bf16 v[68:71], v[160:163], v[208:211], v[68:71]
	v_mfma_f32_16x16x32_bf16 v[64:67], v[168:171], v[208:211], v[64:67]
	v_mfma_f32_16x16x32_bf16 v[116:119], v[164:167], v[188:191], v[116:119]
	v_mfma_f32_16x16x32_bf16 v[112:115], v[172:175], v[188:191], v[112:115]
	v_mfma_f32_16x16x32_bf16 v[100:103], v[164:167], v[196:199], v[100:103]
	v_mfma_f32_16x16x32_bf16 v[96:99], v[172:175], v[196:199], v[96:99]
	s_setprio 2
	s_barrier
	v_mfma_f32_16x16x32_bf16 v[84:87], v[164:167], v[204:207], v[84:87]
	v_mfma_f32_16x16x32_bf16 v[80:83], v[172:175], v[204:207], v[80:83]
	v_mfma_f32_16x16x32_bf16 v[68:71], v[164:167], v[212:215], v[68:71]
	v_mfma_f32_16x16x32_bf16 v[64:67], v[172:175], v[212:215], v[64:67]
	s_setprio 0
	s_add_i32 s44, s74, s51
	v_lshl_add_u64 v[176:177], v[176:177], 0, s[22:23]
	s_mov_b32 m0, s44
	ds_read_b128 v[184:187], v181 offset:49152
	ds_read_b128 v[188:191], v181 offset:50176
	ds_read_b128 v[192:195], v181 offset:51200
	ds_read_b128 v[196:199], v181 offset:52224
	ds_read_b128 v[200:203], v181 offset:53248
	ds_read_b128 v[204:207], v181 offset:54272
	ds_read_b128 v[208:211], v181 offset:55296
	ds_read_b128 v[212:215], v181 offset:56320
	global_load_lds_dwordx4 v[176:177], off
	s_add_i32 m0, s44, 0x2000
	s_add_u32 s40, s40, 0x40080
	v_lshl_add_u64 v[176:177], v[216:217], 0, s[22:23]
	s_addc_u32 s41, s41, 0
	s_add_i32 s44, s75, s51
	global_load_lds_dwordx4 v[176:177], off
	v_lshl_add_u64 v[176:177], s[40:41], 0, v[130:131]
	s_mov_b32 m0, s44
	s_nop 0
	global_load_lds_dwordx4 v[176:177], off
	v_lshl_add_u64 v[176:177], s[40:41], 0, v[134:135]
	s_add_i32 m0, s44, 0x2000
	s_nop 0
	global_load_lds_dwordx4 v[176:177], off
	v_lshl_add_u64 v[176:177], v[218:219], 0, s[22:23]
	s_mov_b32 m0, s64
	s_nop 0
	global_load_lds_dwordx4 v[176:177], off
	v_lshl_add_u64 v[176:177], v[220:221], 0, s[22:23]
	s_mov_b32 m0, s65
	s_nop 0
	global_load_lds_dwordx4 v[176:177], off
	s_waitcnt vmcnt(8)
	s_waitcnt lgkmcnt(0)
	s_barrier
	s_setprio 1
	s_waitcnt lgkmcnt(0)
	v_mfma_f32_16x16x32_bf16 v[60:63], v[144:147], v[184:187], v[60:63]
	v_mfma_f32_16x16x32_bf16 v[56:59], v[152:155], v[184:187], v[56:59]
	v_mfma_f32_16x16x32_bf16 v[44:47], v[144:147], v[192:195], v[44:47]
	v_mfma_f32_16x16x32_bf16 v[40:43], v[152:155], v[192:195], v[40:43]
	v_mfma_f32_16x16x32_bf16 v[28:31], v[144:147], v[200:203], v[28:31]
	v_mfma_f32_16x16x32_bf16 v[24:27], v[152:155], v[200:203], v[24:27]
	v_mfma_f32_16x16x32_bf16 v[12:15], v[144:147], v[208:211], v[12:15]
	v_mfma_f32_16x16x32_bf16 v[8:11], v[152:155], v[208:211], v[8:11]
	v_mfma_f32_16x16x32_bf16 v[60:63], v[148:151], v[188:191], v[60:63]
	v_mfma_f32_16x16x32_bf16 v[56:59], v[156:159], v[188:191], v[56:59]
	v_mfma_f32_16x16x32_bf16 v[44:47], v[148:151], v[196:199], v[44:47]
	v_mfma_f32_16x16x32_bf16 v[40:43], v[156:159], v[196:199], v[40:43]
	v_mfma_f32_16x16x32_bf16 v[28:31], v[148:151], v[204:207], v[28:31]
	v_mfma_f32_16x16x32_bf16 v[24:27], v[156:159], v[204:207], v[24:27]
	v_mfma_f32_16x16x32_bf16 v[12:15], v[148:151], v[212:215], v[12:15]
	v_mfma_f32_16x16x32_bf16 v[8:11], v[156:159], v[212:215], v[8:11]
	s_setprio 0
	s_setprio 1
	v_mfma_f32_16x16x32_bf16 v[52:55], v[160:163], v[184:187], v[52:55]
	v_mfma_f32_16x16x32_bf16 v[48:51], v[168:171], v[184:187], v[48:51]
	v_mfma_f32_16x16x32_bf16 v[36:39], v[160:163], v[192:195], v[36:39]
	v_mfma_f32_16x16x32_bf16 v[32:35], v[168:171], v[192:195], v[32:35]
	v_mfma_f32_16x16x32_bf16 v[20:23], v[160:163], v[200:203], v[20:23]
	v_mfma_f32_16x16x32_bf16 v[16:19], v[168:171], v[200:203], v[16:19]
	v_mfma_f32_16x16x32_bf16 v[4:7], v[160:163], v[208:211], v[4:7]
	v_mfma_f32_16x16x32_bf16 v[0:3], v[168:171], v[208:211], v[0:3]
	v_mfma_f32_16x16x32_bf16 v[52:55], v[164:167], v[188:191], v[52:55]
	v_mfma_f32_16x16x32_bf16 v[48:51], v[172:175], v[188:191], v[48:51]
	v_mfma_f32_16x16x32_bf16 v[36:39], v[164:167], v[196:199], v[36:39]
	v_mfma_f32_16x16x32_bf16 v[32:35], v[172:175], v[196:199], v[32:35]
	s_setprio 2
	s_barrier
	v_mfma_f32_16x16x32_bf16 v[20:23], v[164:167], v[204:207], v[20:23]
	v_mfma_f32_16x16x32_bf16 v[16:19], v[172:175], v[204:207], v[16:19]
	v_mfma_f32_16x16x32_bf16 v[4:7], v[164:167], v[212:215], v[4:7]
	v_mfma_f32_16x16x32_bf16 v[0:3], v[172:175], v[212:215], v[0:3]
	s_setprio 0
	s_add_i32 s73, s73, 2
	s_add_u32 s6, s6, 0x100
	s_addc_u32 s7, s7, 0
	s_add_u32 s71, s71, 0x100
	s_addc_u32 s72, s72, 0
	s_cmp_gt_u32 s73, 13
	s_cbranch_scc0 .LBB0_952

.LBB0_1146:
	ds_read_b128 v[120:123], v233
	ds_read_b128 v[132:135], v233 offset:1024
	ds_read_b128 v[136:139], v233 offset:2048
	ds_read_b128 v[140:143], v233 offset:3072
	ds_read_b128 v[144:147], v234
	ds_read_b128 v[148:151], v234 offset:1024
	ds_read_b128 v[152:155], v234 offset:2048
	ds_read_b128 v[156:159], v234 offset:3072
	s_add_u32 s40, s38, 0xfffc0080
	s_addc_u32 s41, s39, -1
	s_cmp_eq_u32 s66, 12
	s_cselect_b32 s43, s23, s41
	s_cselect_b32 s42, s31, s40
	s_cselect_b32 s41, s25, s65
	s_cselect_b32 s40, s37, s64
	v_lshl_add_u64 v[208:209], s[38:39], 0, v[192:193]
	s_add_i32 m0, s50, 0xc000
	ds_read_b128 v[160:163], v235
	ds_read_b128 v[164:167], v235 offset:1024
	ds_read_b128 v[168:171], v235 offset:2048
	ds_read_b128 v[172:175], v235 offset:3072
	ds_read_b128 v[176:179], v235 offset:4096
	ds_read_b128 v[180:183], v235 offset:5120
	ds_read_b128 v[200:203], v235 offset:6144
	ds_read_b128 v[204:207], v235 offset:7168
	global_load_lds_dwordx4 v[208:209], off
	v_lshl_add_u64 v[208:209], s[38:39], 0, v[194:195]
	s_add_i32 m0, s50, 0xe000
	s_nop 0
	global_load_lds_dwordx4 v[208:209], off
	s_waitcnt vmcnt(8)
	s_waitcnt lgkmcnt(0)
	s_barrier
	s_setprio 1
	s_waitcnt lgkmcnt(0)
	v_mfma_f32_16x16x32_bf16 v[128:131], v[120:123], v[160:163], v[128:131]
	v_mfma_f32_16x16x32_bf16 v[124:127], v[136:139], v[160:163], v[124:127]
	v_mfma_f32_16x16x32_bf16 v[108:111], v[120:123], v[168:171], v[108:111]
	v_mfma_f32_16x16x32_bf16 v[104:107], v[136:139], v[168:171], v[104:107]
	v_mfma_f32_16x16x32_bf16 v[92:95], v[120:123], v[176:179], v[92:95]
	v_mfma_f32_16x16x32_bf16 v[88:91], v[136:139], v[176:179], v[88:91]
	v_mfma_f32_16x16x32_bf16 v[76:79], v[120:123], v[200:203], v[76:79]
	v_mfma_f32_16x16x32_bf16 v[72:75], v[136:139], v[200:203], v[72:75]
	v_mfma_f32_16x16x32_bf16 v[128:131], v[132:135], v[164:167], v[128:131]
	v_mfma_f32_16x16x32_bf16 v[124:127], v[140:143], v[164:167], v[124:127]
	v_mfma_f32_16x16x32_bf16 v[108:111], v[132:135], v[172:175], v[108:111]
	v_mfma_f32_16x16x32_bf16 v[104:107], v[140:143], v[172:175], v[104:107]
	v_mfma_f32_16x16x32_bf16 v[92:95], v[132:135], v[180:183], v[92:95]
	v_mfma_f32_16x16x32_bf16 v[88:91], v[140:143], v[180:183], v[88:91]
	v_mfma_f32_16x16x32_bf16 v[76:79], v[132:135], v[204:207], v[76:79]
	v_mfma_f32_16x16x32_bf16 v[72:75], v[140:143], v[204:207], v[72:75]
	s_setprio 0
	s_setprio 1
	v_mfma_f32_16x16x32_bf16 v[116:119], v[144:147], v[160:163], v[116:119]
	v_mfma_f32_16x16x32_bf16 v[112:115], v[152:155], v[160:163], v[112:115]
	v_mfma_f32_16x16x32_bf16 v[100:103], v[144:147], v[168:171], v[100:103]
	v_mfma_f32_16x16x32_bf16 v[96:99], v[152:155], v[168:171], v[96:99]
	v_mfma_f32_16x16x32_bf16 v[84:87], v[144:147], v[176:179], v[84:87]
	v_mfma_f32_16x16x32_bf16 v[80:83], v[152:155], v[176:179], v[80:83]
	v_mfma_f32_16x16x32_bf16 v[68:71], v[144:147], v[200:203], v[68:71]
	v_mfma_f32_16x16x32_bf16 v[64:67], v[152:155], v[200:203], v[64:67]
	v_mfma_f32_16x16x32_bf16 v[116:119], v[148:151], v[164:167], v[116:119]
	v_mfma_f32_16x16x32_bf16 v[112:115], v[156:159], v[164:167], v[112:115]
	v_mfma_f32_16x16x32_bf16 v[100:103], v[148:151], v[172:175], v[100:103]
	v_mfma_f32_16x16x32_bf16 v[96:99], v[156:159], v[172:175], v[96:99]
	s_setprio 2
	s_barrier
	v_mfma_f32_16x16x32_bf16 v[84:87], v[148:151], v[180:183], v[84:87]
	v_mfma_f32_16x16x32_bf16 v[80:83], v[156:159], v[180:183], v[80:83]
	v_mfma_f32_16x16x32_bf16 v[68:71], v[148:151], v[204:207], v[68:71]
	v_mfma_f32_16x16x32_bf16 v[64:67], v[156:159], v[204:207], v[64:67]
	s_setprio 0
	s_add_i32 s67, s62, s49
	v_lshl_add_u64 v[208:209], s[40:41], 0, v[186:187]
	s_mov_b32 m0, s67
	ds_read_b128 v[160:163], v235 offset:16384
	ds_read_b128 v[164:167], v235 offset:17408
	ds_read_b128 v[168:171], v235 offset:18432
	ds_read_b128 v[172:175], v235 offset:19456
	ds_read_b128 v[176:179], v235 offset:20480
	ds_read_b128 v[180:183], v235 offset:21504
	ds_read_b128 v[200:203], v235 offset:22528
	ds_read_b128 v[204:207], v235 offset:23552
	global_load_lds_dwordx4 v[208:209], off
	s_add_i32 m0, s67, 0x2000
	s_add_u32 s68, s40, 0x40000
	v_lshl_add_u64 v[210:211], s[40:41], 0, v[190:191]
	s_addc_u32 s69, s41, 0
	s_add_i32 s67, s63, s49
	global_load_lds_dwordx4 v[210:211], off
	v_lshl_add_u64 v[212:213], s[68:69], 0, v[186:187]
	s_mov_b32 m0, s67
	v_lshl_add_u64 v[214:215], s[42:43], 0, v[188:189]
	global_load_lds_dwordx4 v[212:213], off
	v_lshl_add_u64 v[212:213], s[42:43], 0, v[184:185]
	s_mov_b32 m0, s50
	s_nop 0
	global_load_lds_dwordx4 v[212:213], off
	s_mov_b32 m0, s51
	s_nop 0
	global_load_lds_dwordx4 v[214:215], off
	s_waitcnt vmcnt(7)
	s_waitcnt lgkmcnt(0)
	s_barrier
	s_setprio 1
	s_waitcnt lgkmcnt(0)
	v_mfma_f32_16x16x32_bf16 v[60:63], v[120:123], v[160:163], v[60:63]
	v_mfma_f32_16x16x32_bf16 v[56:59], v[136:139], v[160:163], v[56:59]
	v_mfma_f32_16x16x32_bf16 v[44:47], v[120:123], v[168:171], v[44:47]
	v_mfma_f32_16x16x32_bf16 v[40:43], v[136:139], v[168:171], v[40:43]
	v_mfma_f32_16x16x32_bf16 v[28:31], v[120:123], v[176:179], v[28:31]
	v_mfma_f32_16x16x32_bf16 v[24:27], v[136:139], v[176:179], v[24:27]
	v_mfma_f32_16x16x32_bf16 v[12:15], v[120:123], v[200:203], v[12:15]
	v_mfma_f32_16x16x32_bf16 v[8:11], v[136:139], v[200:203], v[8:11]
	v_mfma_f32_16x16x32_bf16 v[60:63], v[132:135], v[164:167], v[60:63]
	v_mfma_f32_16x16x32_bf16 v[56:59], v[140:143], v[164:167], v[56:59]
	v_mfma_f32_16x16x32_bf16 v[44:47], v[132:135], v[172:175], v[44:47]
	v_mfma_f32_16x16x32_bf16 v[40:43], v[140:143], v[172:175], v[40:43]
	v_mfma_f32_16x16x32_bf16 v[28:31], v[132:135], v[180:183], v[28:31]
	v_mfma_f32_16x16x32_bf16 v[24:27], v[140:143], v[180:183], v[24:27]
	v_mfma_f32_16x16x32_bf16 v[12:15], v[132:135], v[204:207], v[12:15]
	v_mfma_f32_16x16x32_bf16 v[8:11], v[140:143], v[204:207], v[8:11]
	s_setprio 0
	s_setprio 1
	v_mfma_f32_16x16x32_bf16 v[52:55], v[144:147], v[160:163], v[52:55]
	v_mfma_f32_16x16x32_bf16 v[48:51], v[152:155], v[160:163], v[48:51]
	v_mfma_f32_16x16x32_bf16 v[36:39], v[144:147], v[168:171], v[36:39]
	v_mfma_f32_16x16x32_bf16 v[32:35], v[152:155], v[168:171], v[32:35]
	v_mfma_f32_16x16x32_bf16 v[20:23], v[144:147], v[176:179], v[20:23]
	v_mfma_f32_16x16x32_bf16 v[16:19], v[152:155], v[176:179], v[16:19]
	v_mfma_f32_16x16x32_bf16 v[4:7], v[144:147], v[200:203], v[4:7]
	v_mfma_f32_16x16x32_bf16 v[0:3], v[152:155], v[200:203], v[0:3]
	v_mfma_f32_16x16x32_bf16 v[52:55], v[148:151], v[164:167], v[52:55]
	v_mfma_f32_16x16x32_bf16 v[48:51], v[156:159], v[164:167], v[48:51]
	v_mfma_f32_16x16x32_bf16 v[36:39], v[148:151], v[172:175], v[36:39]
	v_mfma_f32_16x16x32_bf16 v[32:35], v[156:159], v[172:175], v[32:35]
	s_setprio 2
	s_barrier
	v_mfma_f32_16x16x32_bf16 v[20:23], v[148:151], v[180:183], v[20:23]
	v_mfma_f32_16x16x32_bf16 v[16:19], v[156:159], v[180:183], v[16:19]
	v_mfma_f32_16x16x32_bf16 v[4:7], v[148:151], v[204:207], v[4:7]
	v_mfma_f32_16x16x32_bf16 v[0:3], v[156:159], v[204:207], v[0:3]
	s_setprio 0
	v_lshl_add_u64 v[252:253], s[68:69], 0, v[190:191]
	s_add_i32 m0, s67, 0x2000
	s_nop 0
	global_load_lds_dwordx4 v[252:253], off
	s_add_i32 s67, 0, 0x18000
	s_add_i32 s68, 0, 0x1c000
	v_add_u32_e32 v140, s67, v232
	v_add_u32_e32 v156, s68, v232
	ds_read_b128 v[120:123], v140
	ds_read_b128 v[132:135], v140 offset:1024
	ds_read_b128 v[136:139], v140 offset:2048
	ds_read_b128 v[140:143], v140 offset:3072
	ds_read_b128 v[144:147], v156
	ds_read_b128 v[148:151], v156 offset:1024
	ds_read_b128 v[152:155], v156 offset:2048
	ds_read_b128 v[156:159], v156 offset:3072
	s_add_u32 s42, s42, 0x40000
	s_addc_u32 s43, s43, 0
	s_mov_b32 m0, s54
	v_lshl_add_u64 v[216:217], s[42:43], 0, v[184:185]
	ds_read_b128 v[160:163], v235 offset:32768
	ds_read_b128 v[164:167], v235 offset:33792
	ds_read_b128 v[168:171], v235 offset:34816
	ds_read_b128 v[172:175], v235 offset:35840
	ds_read_b128 v[176:179], v235 offset:36864
	ds_read_b128 v[180:183], v235 offset:37888
	ds_read_b128 v[200:203], v235 offset:38912
	ds_read_b128 v[204:207], v235 offset:39936
	global_load_lds_dwordx4 v[216:217], off
	v_lshl_add_u64 v[216:217], s[42:43], 0, v[188:189]
	s_mov_b32 m0, s55
	s_nop 0
	global_load_lds_dwordx4 v[216:217], off
	s_waitcnt vmcnt(8)
	s_waitcnt lgkmcnt(0)
	s_barrier
	s_setprio 1
	s_waitcnt lgkmcnt(0)
	v_mfma_f32_16x16x32_bf16 v[128:131], v[120:123], v[160:163], v[128:131]
	v_mfma_f32_16x16x32_bf16 v[124:127], v[136:139], v[160:163], v[124:127]
	v_mfma_f32_16x16x32_bf16 v[108:111], v[120:123], v[168:171], v[108:111]
	v_mfma_f32_16x16x32_bf16 v[104:107], v[136:139], v[168:171], v[104:107]
	v_mfma_f32_16x16x32_bf16 v[92:95], v[120:123], v[176:179], v[92:95]
	v_mfma_f32_16x16x32_bf16 v[88:91], v[136:139], v[176:179], v[88:91]
	v_mfma_f32_16x16x32_bf16 v[76:79], v[120:123], v[200:203], v[76:79]
	v_mfma_f32_16x16x32_bf16 v[72:75], v[136:139], v[200:203], v[72:75]
	v_mfma_f32_16x16x32_bf16 v[128:131], v[132:135], v[164:167], v[128:131]
	v_mfma_f32_16x16x32_bf16 v[124:127], v[140:143], v[164:167], v[124:127]
	v_mfma_f32_16x16x32_bf16 v[108:111], v[132:135], v[172:175], v[108:111]
	v_mfma_f32_16x16x32_bf16 v[104:107], v[140:143], v[172:175], v[104:107]
	v_mfma_f32_16x16x32_bf16 v[92:95], v[132:135], v[180:183], v[92:95]
	v_mfma_f32_16x16x32_bf16 v[88:91], v[140:143], v[180:183], v[88:91]
	v_mfma_f32_16x16x32_bf16 v[76:79], v[132:135], v[204:207], v[76:79]
	v_mfma_f32_16x16x32_bf16 v[72:75], v[140:143], v[204:207], v[72:75]
	s_setprio 0
	s_setprio 1
	v_mfma_f32_16x16x32_bf16 v[116:119], v[144:147], v[160:163], v[116:119]
	v_mfma_f32_16x16x32_bf16 v[112:115], v[152:155], v[160:163], v[112:115]
	v_mfma_f32_16x16x32_bf16 v[100:103], v[144:147], v[168:171], v[100:103]
	v_mfma_f32_16x16x32_bf16 v[96:99], v[152:155], v[168:171], v[96:99]
	v_mfma_f32_16x16x32_bf16 v[84:87], v[144:147], v[176:179], v[84:87]
	v_mfma_f32_16x16x32_bf16 v[80:83], v[152:155], v[176:179], v[80:83]
	v_mfma_f32_16x16x32_bf16 v[68:71], v[144:147], v[200:203], v[68:71]
	v_mfma_f32_16x16x32_bf16 v[64:67], v[152:155], v[200:203], v[64:67]
	v_mfma_f32_16x16x32_bf16 v[116:119], v[148:151], v[164:167], v[116:119]
	v_mfma_f32_16x16x32_bf16 v[112:115], v[156:159], v[164:167], v[112:115]
	v_mfma_f32_16x16x32_bf16 v[100:103], v[148:151], v[172:175], v[100:103]
	v_mfma_f32_16x16x32_bf16 v[96:99], v[156:159], v[172:175], v[96:99]
	s_setprio 2
	s_barrier
	v_mfma_f32_16x16x32_bf16 v[84:87], v[148:151], v[180:183], v[84:87]
	v_mfma_f32_16x16x32_bf16 v[80:83], v[156:159], v[180:183], v[80:83]
	v_mfma_f32_16x16x32_bf16 v[68:71], v[148:151], v[204:207], v[68:71]
	v_mfma_f32_16x16x32_bf16 v[64:67], v[156:159], v[204:207], v[64:67]
	s_setprio 0
	s_add_i32 s42, s67, s49
	v_lshl_add_u64 v[208:209], v[208:209], 0, s[18:19]
	s_mov_b32 m0, s42
	ds_read_b128 v[160:163], v235 offset:49152
	ds_read_b128 v[164:167], v235 offset:50176
	ds_read_b128 v[168:171], v235 offset:51200
	ds_read_b128 v[172:175], v235 offset:52224
	ds_read_b128 v[176:179], v235 offset:53248
	ds_read_b128 v[180:183], v235 offset:54272
	ds_read_b128 v[200:203], v235 offset:55296
	ds_read_b128 v[204:207], v235 offset:56320
	global_load_lds_dwordx4 v[208:209], off
	s_add_i32 m0, s42, 0x2000
	s_add_u32 s40, s40, 0x40080
	v_lshl_add_u64 v[208:209], v[210:211], 0, s[18:19]
	s_addc_u32 s41, s41, 0
	s_add_i32 s42, s68, s49
	global_load_lds_dwordx4 v[208:209], off
	v_lshl_add_u64 v[208:209], s[40:41], 0, v[186:187]
	s_mov_b32 m0, s42
	s_nop 0
	global_load_lds_dwordx4 v[208:209], off
	v_lshl_add_u64 v[208:209], s[40:41], 0, v[190:191]
	s_add_i32 m0, s42, 0x2000
	s_nop 0
	global_load_lds_dwordx4 v[208:209], off
	v_lshl_add_u64 v[208:209], v[212:213], 0, s[18:19]
	s_mov_b32 m0, s57
	s_nop 0
	global_load_lds_dwordx4 v[208:209], off
	v_lshl_add_u64 v[208:209], v[214:215], 0, s[18:19]
	s_mov_b32 m0, s58
	s_nop 0
	global_load_lds_dwordx4 v[208:209], off
	s_waitcnt vmcnt(8)
	s_waitcnt lgkmcnt(0)
	s_barrier
	s_setprio 1
	s_waitcnt lgkmcnt(0)
	v_mfma_f32_16x16x32_bf16 v[60:63], v[120:123], v[160:163], v[60:63]
	v_mfma_f32_16x16x32_bf16 v[56:59], v[136:139], v[160:163], v[56:59]
	v_mfma_f32_16x16x32_bf16 v[44:47], v[120:123], v[168:171], v[44:47]
	v_mfma_f32_16x16x32_bf16 v[40:43], v[136:139], v[168:171], v[40:43]
	v_mfma_f32_16x16x32_bf16 v[28:31], v[120:123], v[176:179], v[28:31]
	v_mfma_f32_16x16x32_bf16 v[24:27], v[136:139], v[176:179], v[24:27]
	v_mfma_f32_16x16x32_bf16 v[12:15], v[120:123], v[200:203], v[12:15]
	v_mfma_f32_16x16x32_bf16 v[8:11], v[136:139], v[200:203], v[8:11]
	v_mfma_f32_16x16x32_bf16 v[60:63], v[132:135], v[164:167], v[60:63]
	v_mfma_f32_16x16x32_bf16 v[56:59], v[140:143], v[164:167], v[56:59]
	v_mfma_f32_16x16x32_bf16 v[44:47], v[132:135], v[172:175], v[44:47]
	v_mfma_f32_16x16x32_bf16 v[40:43], v[140:143], v[172:175], v[40:43]
	v_mfma_f32_16x16x32_bf16 v[28:31], v[132:135], v[180:183], v[28:31]
	v_mfma_f32_16x16x32_bf16 v[24:27], v[140:143], v[180:183], v[24:27]
	v_mfma_f32_16x16x32_bf16 v[12:15], v[132:135], v[204:207], v[12:15]
	v_mfma_f32_16x16x32_bf16 v[8:11], v[140:143], v[204:207], v[8:11]
	s_setprio 0
	s_setprio 1
	v_mfma_f32_16x16x32_bf16 v[52:55], v[144:147], v[160:163], v[52:55]
	v_mfma_f32_16x16x32_bf16 v[48:51], v[152:155], v[160:163], v[48:51]
	v_mfma_f32_16x16x32_bf16 v[36:39], v[144:147], v[168:171], v[36:39]
	v_mfma_f32_16x16x32_bf16 v[32:35], v[152:155], v[168:171], v[32:35]
	v_mfma_f32_16x16x32_bf16 v[20:23], v[144:147], v[176:179], v[20:23]
	v_mfma_f32_16x16x32_bf16 v[16:19], v[152:155], v[176:179], v[16:19]
	v_mfma_f32_16x16x32_bf16 v[4:7], v[144:147], v[200:203], v[4:7]
	v_mfma_f32_16x16x32_bf16 v[0:3], v[152:155], v[200:203], v[0:3]
	v_mfma_f32_16x16x32_bf16 v[52:55], v[148:151], v[164:167], v[52:55]
	v_mfma_f32_16x16x32_bf16 v[48:51], v[156:159], v[164:167], v[48:51]
	v_mfma_f32_16x16x32_bf16 v[36:39], v[148:151], v[172:175], v[36:39]
	v_mfma_f32_16x16x32_bf16 v[32:35], v[156:159], v[172:175], v[32:35]
	s_setprio 2
	s_barrier
	v_mfma_f32_16x16x32_bf16 v[20:23], v[148:151], v[180:183], v[20:23]
	v_mfma_f32_16x16x32_bf16 v[16:19], v[156:159], v[180:183], v[16:19]
	v_mfma_f32_16x16x32_bf16 v[4:7], v[148:151], v[204:207], v[4:7]
	v_mfma_f32_16x16x32_bf16 v[0:3], v[156:159], v[204:207], v[0:3]
	s_setprio 0
	s_add_i32 s66, s66, 2
	s_add_u32 s38, s38, 0x100
	s_addc_u32 s39, s39, 0
	s_add_u32 s64, s64, 0x100
	s_addc_u32 s65, s65, 0
	s_cmp_gt_u32 s66, 13
	s_cbranch_scc0 .LBB0_1146

.LBB0_1310:
	ds_read_b128 v[128:131], v197
	ds_read_b128 v[132:135], v197 offset:1024
	ds_read_b128 v[136:139], v197 offset:2048
	ds_read_b128 v[140:143], v197 offset:3072
	ds_read_b128 v[144:147], v198
	ds_read_b128 v[148:151], v198 offset:1024
	ds_read_b128 v[152:155], v198 offset:2048
	ds_read_b128 v[156:159], v198 offset:3072
	s_add_u32 s4, s24, 0x100
	s_addc_u32 s5, s25, 0
	s_cmp_eq_u32 s53, 40
	s_cselect_b32 s29, s21, s5
	s_cselect_b32 s28, s20, s4
	s_cselect_b32 s27, s23, s52
	s_cselect_b32 s26, s22, s51
	v_lshl_add_u64 v[212:213], s[24:25], 0, v[172:173]
	s_add_i32 m0, s36, 0xc000
	ds_read_b128 v[160:163], v199
	ds_read_b128 v[180:183], v199 offset:1024
	ds_read_b128 v[184:187], v199 offset:2048
	ds_read_b128 v[188:191], v199 offset:3072
	ds_read_b128 v[192:195], v199 offset:4096
	ds_read_b128 v[200:203], v199 offset:5120
	ds_read_b128 v[204:207], v199 offset:6144
	ds_read_b128 v[208:211], v199 offset:7168
	global_load_lds_dwordx4 v[212:213], off
	v_lshl_add_u64 v[212:213], s[24:25], 0, v[174:175]
	s_add_i32 m0, s36, 0xe000
	s_nop 0
	global_load_lds_dwordx4 v[212:213], off
	s_waitcnt vmcnt(8)
	s_waitcnt lgkmcnt(0)
	s_barrier
	s_setprio 1
	s_waitcnt lgkmcnt(0)
	v_mfma_f32_16x16x32_bf16 v[124:127], v[128:131], v[160:163], v[124:127]
	v_mfma_f32_16x16x32_bf16 v[120:123], v[136:139], v[160:163], v[120:123]
	v_mfma_f32_16x16x32_bf16 v[116:119], v[128:131], v[184:187], v[116:119]
	v_mfma_f32_16x16x32_bf16 v[108:111], v[136:139], v[184:187], v[108:111]
	v_mfma_f32_16x16x32_bf16 v[88:91], v[128:131], v[192:195], v[88:91]
	v_mfma_f32_16x16x32_bf16 v[100:103], v[136:139], v[192:195], v[100:103]
	v_mfma_f32_16x16x32_bf16 v[72:75], v[128:131], v[204:207], v[72:75]
	v_mfma_f32_16x16x32_bf16 v[76:79], v[136:139], v[204:207], v[76:79]
	v_mfma_f32_16x16x32_bf16 v[124:127], v[132:135], v[180:183], v[124:127]
	v_mfma_f32_16x16x32_bf16 v[120:123], v[140:143], v[180:183], v[120:123]
	v_mfma_f32_16x16x32_bf16 v[116:119], v[132:135], v[188:191], v[116:119]
	v_mfma_f32_16x16x32_bf16 v[108:111], v[140:143], v[188:191], v[108:111]
	v_mfma_f32_16x16x32_bf16 v[88:91], v[132:135], v[200:203], v[88:91]
	v_mfma_f32_16x16x32_bf16 v[100:103], v[140:143], v[200:203], v[100:103]
	v_mfma_f32_16x16x32_bf16 v[72:75], v[132:135], v[208:211], v[72:75]
	v_mfma_f32_16x16x32_bf16 v[76:79], v[140:143], v[208:211], v[76:79]
	s_setprio 0
	s_setprio 1
	v_mfma_f32_16x16x32_bf16 v[112:115], v[144:147], v[160:163], v[112:115]
	v_mfma_f32_16x16x32_bf16 v[104:107], v[152:155], v[160:163], v[104:107]
	v_mfma_f32_16x16x32_bf16 v[96:99], v[144:147], v[184:187], v[96:99]
	v_mfma_f32_16x16x32_bf16 v[92:95], v[152:155], v[184:187], v[92:95]
	v_mfma_f32_16x16x32_bf16 v[80:83], v[144:147], v[192:195], v[80:83]
	v_mfma_f32_16x16x32_bf16 v[84:87], v[152:155], v[192:195], v[84:87]
	v_mfma_f32_16x16x32_bf16 v[64:67], v[144:147], v[204:207], v[64:67]
	v_mfma_f32_16x16x32_bf16 v[68:71], v[152:155], v[204:207], v[68:71]
	v_mfma_f32_16x16x32_bf16 v[112:115], v[148:151], v[180:183], v[112:115]
	v_mfma_f32_16x16x32_bf16 v[104:107], v[156:159], v[180:183], v[104:107]
	v_mfma_f32_16x16x32_bf16 v[96:99], v[148:151], v[188:191], v[96:99]
	v_mfma_f32_16x16x32_bf16 v[92:95], v[156:159], v[188:191], v[92:95]
	s_setprio 2
	s_barrier
	v_mfma_f32_16x16x32_bf16 v[80:83], v[148:151], v[200:203], v[80:83]
	v_mfma_f32_16x16x32_bf16 v[84:87], v[156:159], v[200:203], v[84:87]
	v_mfma_f32_16x16x32_bf16 v[64:67], v[148:151], v[208:211], v[64:67]
	v_mfma_f32_16x16x32_bf16 v[68:71], v[156:159], v[208:211], v[68:71]
	s_setprio 0
	s_add_i32 s24, s45, s35
	v_lshl_add_u64 v[212:213], s[26:27], 0, v[166:167]
	s_mov_b32 m0, s24
	ds_read_b128 v[160:163], v199 offset:16384
	ds_read_b128 v[180:183], v199 offset:17408
	ds_read_b128 v[184:187], v199 offset:18432
	ds_read_b128 v[188:191], v199 offset:19456
	ds_read_b128 v[192:195], v199 offset:20480
	ds_read_b128 v[200:203], v199 offset:21504
	ds_read_b128 v[204:207], v199 offset:22528
	ds_read_b128 v[208:211], v199 offset:23552
	global_load_lds_dwordx4 v[212:213], off
	s_add_i32 m0, s24, 0x2000
	s_add_u32 s24, s26, 0xb0000
	v_lshl_add_u64 v[214:215], s[26:27], 0, v[170:171]
	s_addc_u32 s25, s27, 0
	s_add_i32 s54, s46, s35
	global_load_lds_dwordx4 v[214:215], off
	v_lshl_add_u64 v[216:217], s[24:25], 0, v[166:167]
	s_mov_b32 m0, s54
	v_lshl_add_u64 v[218:219], s[28:29], 0, v[168:169]
	global_load_lds_dwordx4 v[216:217], off
	v_lshl_add_u64 v[216:217], s[28:29], 0, v[164:165]
	s_mov_b32 m0, s36
	s_nop 0
	global_load_lds_dwordx4 v[216:217], off
	s_mov_b32 m0, s37
	s_nop 0
	global_load_lds_dwordx4 v[218:219], off
	s_waitcnt vmcnt(7)
	s_waitcnt lgkmcnt(0)
	s_barrier
	s_setprio 1
	s_waitcnt lgkmcnt(0)
	v_mfma_f32_16x16x32_bf16 v[56:59], v[128:131], v[160:163], v[56:59]
	v_mfma_f32_16x16x32_bf16 v[60:63], v[136:139], v[160:163], v[60:63]
	v_mfma_f32_16x16x32_bf16 v[40:43], v[128:131], v[184:187], v[40:43]
	v_mfma_f32_16x16x32_bf16 v[44:47], v[136:139], v[184:187], v[44:47]
	v_mfma_f32_16x16x32_bf16 v[24:27], v[128:131], v[192:195], v[24:27]
	v_mfma_f32_16x16x32_bf16 v[28:31], v[136:139], v[192:195], v[28:31]
	v_mfma_f32_16x16x32_bf16 v[8:11], v[128:131], v[204:207], v[8:11]
	v_mfma_f32_16x16x32_bf16 v[12:15], v[136:139], v[204:207], v[12:15]
	v_mfma_f32_16x16x32_bf16 v[56:59], v[132:135], v[180:183], v[56:59]
	v_mfma_f32_16x16x32_bf16 v[60:63], v[140:143], v[180:183], v[60:63]
	v_mfma_f32_16x16x32_bf16 v[40:43], v[132:135], v[188:191], v[40:43]
	v_mfma_f32_16x16x32_bf16 v[44:47], v[140:143], v[188:191], v[44:47]
	v_mfma_f32_16x16x32_bf16 v[24:27], v[132:135], v[200:203], v[24:27]
	v_mfma_f32_16x16x32_bf16 v[28:31], v[140:143], v[200:203], v[28:31]
	v_mfma_f32_16x16x32_bf16 v[8:11], v[132:135], v[208:211], v[8:11]
	v_mfma_f32_16x16x32_bf16 v[12:15], v[140:143], v[208:211], v[12:15]
	s_setprio 0
	s_setprio 1
	v_mfma_f32_16x16x32_bf16 v[48:51], v[144:147], v[160:163], v[48:51]
	v_mfma_f32_16x16x32_bf16 v[52:55], v[152:155], v[160:163], v[52:55]
	v_mfma_f32_16x16x32_bf16 v[32:35], v[144:147], v[184:187], v[32:35]
	v_mfma_f32_16x16x32_bf16 v[36:39], v[152:155], v[184:187], v[36:39]
	v_mfma_f32_16x16x32_bf16 v[16:19], v[144:147], v[192:195], v[16:19]
	v_mfma_f32_16x16x32_bf16 v[20:23], v[152:155], v[192:195], v[20:23]
	v_mfma_f32_16x16x32_bf16 v[0:3], v[144:147], v[204:207], v[0:3]
	v_mfma_f32_16x16x32_bf16 v[4:7], v[152:155], v[204:207], v[4:7]
	v_mfma_f32_16x16x32_bf16 v[48:51], v[148:151], v[180:183], v[48:51]
	v_mfma_f32_16x16x32_bf16 v[52:55], v[156:159], v[180:183], v[52:55]
	v_mfma_f32_16x16x32_bf16 v[32:35], v[148:151], v[188:191], v[32:35]
	v_mfma_f32_16x16x32_bf16 v[36:39], v[156:159], v[188:191], v[36:39]
	s_setprio 2
	s_barrier
	v_mfma_f32_16x16x32_bf16 v[16:19], v[148:151], v[200:203], v[16:19]
	v_mfma_f32_16x16x32_bf16 v[20:23], v[156:159], v[200:203], v[20:23]
	v_mfma_f32_16x16x32_bf16 v[0:3], v[148:151], v[208:211], v[0:3]
	v_mfma_f32_16x16x32_bf16 v[4:7], v[156:159], v[208:211], v[4:7]
	s_setprio 0
	v_lshl_add_u64 v[252:253], s[24:25], 0, v[170:171]
	s_add_i32 m0, s54, 0x2000
	s_nop 0
	global_load_lds_dwordx4 v[252:253], off
	s_add_i32 s54, 0, 0x18000
	s_add_i32 s55, 0, 0x1c000
	v_add_u32_e32 v140, s54, v196
	v_add_u32_e32 v156, s55, v196
	ds_read_b128 v[128:131], v140
	ds_read_b128 v[132:135], v140 offset:1024
	ds_read_b128 v[136:139], v140 offset:2048
	ds_read_b128 v[140:143], v140 offset:3072
	ds_read_b128 v[144:147], v156
	ds_read_b128 v[148:151], v156 offset:1024
	ds_read_b128 v[152:155], v156 offset:2048
	ds_read_b128 v[156:159], v156 offset:3072
	s_add_u32 s24, s28, 0xb0000
	s_addc_u32 s25, s29, 0
	s_mov_b32 m0, s38
	v_lshl_add_u64 v[220:221], s[24:25], 0, v[164:165]
	ds_read_b128 v[160:163], v199 offset:32768
	ds_read_b128 v[180:183], v199 offset:33792
	ds_read_b128 v[184:187], v199 offset:34816
	ds_read_b128 v[188:191], v199 offset:35840
	ds_read_b128 v[192:195], v199 offset:36864
	ds_read_b128 v[200:203], v199 offset:37888
	ds_read_b128 v[204:207], v199 offset:38912
	ds_read_b128 v[208:211], v199 offset:39936
	global_load_lds_dwordx4 v[220:221], off
	v_lshl_add_u64 v[220:221], s[24:25], 0, v[168:169]
	s_mov_b32 m0, s39
	s_nop 0
	global_load_lds_dwordx4 v[220:221], off
	s_waitcnt vmcnt(8)
	s_waitcnt lgkmcnt(0)
	s_barrier
	s_setprio 1
	s_waitcnt lgkmcnt(0)
	v_mfma_f32_16x16x32_bf16 v[124:127], v[128:131], v[160:163], v[124:127]
	v_mfma_f32_16x16x32_bf16 v[120:123], v[136:139], v[160:163], v[120:123]
	v_mfma_f32_16x16x32_bf16 v[116:119], v[128:131], v[184:187], v[116:119]
	v_mfma_f32_16x16x32_bf16 v[108:111], v[136:139], v[184:187], v[108:111]
	v_mfma_f32_16x16x32_bf16 v[88:91], v[128:131], v[192:195], v[88:91]
	v_mfma_f32_16x16x32_bf16 v[100:103], v[136:139], v[192:195], v[100:103]
	v_mfma_f32_16x16x32_bf16 v[72:75], v[128:131], v[204:207], v[72:75]
	v_mfma_f32_16x16x32_bf16 v[76:79], v[136:139], v[204:207], v[76:79]
	v_mfma_f32_16x16x32_bf16 v[124:127], v[132:135], v[180:183], v[124:127]
	v_mfma_f32_16x16x32_bf16 v[120:123], v[140:143], v[180:183], v[120:123]
	v_mfma_f32_16x16x32_bf16 v[116:119], v[132:135], v[188:191], v[116:119]
	v_mfma_f32_16x16x32_bf16 v[108:111], v[140:143], v[188:191], v[108:111]
	v_mfma_f32_16x16x32_bf16 v[88:91], v[132:135], v[200:203], v[88:91]
	v_mfma_f32_16x16x32_bf16 v[100:103], v[140:143], v[200:203], v[100:103]
	v_mfma_f32_16x16x32_bf16 v[72:75], v[132:135], v[208:211], v[72:75]
	v_mfma_f32_16x16x32_bf16 v[76:79], v[140:143], v[208:211], v[76:79]
	s_setprio 0
	s_setprio 1
	v_mfma_f32_16x16x32_bf16 v[112:115], v[144:147], v[160:163], v[112:115]
	v_mfma_f32_16x16x32_bf16 v[104:107], v[152:155], v[160:163], v[104:107]
	v_mfma_f32_16x16x32_bf16 v[96:99], v[144:147], v[184:187], v[96:99]
	v_mfma_f32_16x16x32_bf16 v[92:95], v[152:155], v[184:187], v[92:95]
	v_mfma_f32_16x16x32_bf16 v[80:83], v[144:147], v[192:195], v[80:83]
	v_mfma_f32_16x16x32_bf16 v[84:87], v[152:155], v[192:195], v[84:87]
	v_mfma_f32_16x16x32_bf16 v[64:67], v[144:147], v[204:207], v[64:67]
	v_mfma_f32_16x16x32_bf16 v[68:71], v[152:155], v[204:207], v[68:71]
	v_mfma_f32_16x16x32_bf16 v[112:115], v[148:151], v[180:183], v[112:115]
	v_mfma_f32_16x16x32_bf16 v[104:107], v[156:159], v[180:183], v[104:107]
	v_mfma_f32_16x16x32_bf16 v[96:99], v[148:151], v[188:191], v[96:99]
	v_mfma_f32_16x16x32_bf16 v[92:95], v[156:159], v[188:191], v[92:95]
	s_setprio 2
	s_barrier
	v_mfma_f32_16x16x32_bf16 v[80:83], v[148:151], v[200:203], v[80:83]
	v_mfma_f32_16x16x32_bf16 v[84:87], v[156:159], v[200:203], v[84:87]
	v_mfma_f32_16x16x32_bf16 v[64:67], v[148:151], v[208:211], v[64:67]
	v_mfma_f32_16x16x32_bf16 v[68:71], v[156:159], v[208:211], v[68:71]
	s_setprio 0
	s_add_i32 s24, s54, s35
	v_lshl_add_u64 v[212:213], v[212:213], 0, s[16:17]
	s_mov_b32 m0, s24
	ds_read_b128 v[160:163], v199 offset:49152
	ds_read_b128 v[180:183], v199 offset:50176
	ds_read_b128 v[184:187], v199 offset:51200
	ds_read_b128 v[188:191], v199 offset:52224
	ds_read_b128 v[192:195], v199 offset:53248
	ds_read_b128 v[200:203], v199 offset:54272
	ds_read_b128 v[204:207], v199 offset:55296
	ds_read_b128 v[208:211], v199 offset:56320
	global_load_lds_dwordx4 v[212:213], off
	s_add_i32 m0, s24, 0x2000
	s_add_u32 s24, s26, 0xb0080
	v_lshl_add_u64 v[212:213], v[214:215], 0, s[16:17]
	s_addc_u32 s25, s27, 0
	s_add_i32 s26, s55, s35
	global_load_lds_dwordx4 v[212:213], off
	v_lshl_add_u64 v[212:213], s[24:25], 0, v[166:167]
	s_mov_b32 m0, s26
	s_nop 0
	global_load_lds_dwordx4 v[212:213], off
	v_lshl_add_u64 v[212:213], s[24:25], 0, v[170:171]
	s_add_i32 m0, s26, 0x2000
	s_nop 0
	global_load_lds_dwordx4 v[212:213], off
	v_lshl_add_u64 v[212:213], v[216:217], 0, s[16:17]
	s_mov_b32 m0, s41
	s_nop 0
	global_load_lds_dwordx4 v[212:213], off
	v_lshl_add_u64 v[212:213], v[218:219], 0, s[16:17]
	s_mov_b32 m0, s42
	s_nop 0
	global_load_lds_dwordx4 v[212:213], off
	s_waitcnt vmcnt(8)
	s_waitcnt lgkmcnt(0)
	s_barrier
	s_setprio 1
	s_waitcnt lgkmcnt(0)
	v_mfma_f32_16x16x32_bf16 v[56:59], v[128:131], v[160:163], v[56:59]
	v_mfma_f32_16x16x32_bf16 v[60:63], v[136:139], v[160:163], v[60:63]
	v_mfma_f32_16x16x32_bf16 v[40:43], v[128:131], v[184:187], v[40:43]
	v_mfma_f32_16x16x32_bf16 v[44:47], v[136:139], v[184:187], v[44:47]
	v_mfma_f32_16x16x32_bf16 v[24:27], v[128:131], v[192:195], v[24:27]
	v_mfma_f32_16x16x32_bf16 v[28:31], v[136:139], v[192:195], v[28:31]
	v_mfma_f32_16x16x32_bf16 v[8:11], v[128:131], v[204:207], v[8:11]
	v_mfma_f32_16x16x32_bf16 v[12:15], v[136:139], v[204:207], v[12:15]
	v_mfma_f32_16x16x32_bf16 v[56:59], v[132:135], v[180:183], v[56:59]
	v_mfma_f32_16x16x32_bf16 v[60:63], v[140:143], v[180:183], v[60:63]
	v_mfma_f32_16x16x32_bf16 v[40:43], v[132:135], v[188:191], v[40:43]
	v_mfma_f32_16x16x32_bf16 v[44:47], v[140:143], v[188:191], v[44:47]
	v_mfma_f32_16x16x32_bf16 v[24:27], v[132:135], v[200:203], v[24:27]
	v_mfma_f32_16x16x32_bf16 v[28:31], v[140:143], v[200:203], v[28:31]
	v_mfma_f32_16x16x32_bf16 v[8:11], v[132:135], v[208:211], v[8:11]
	v_mfma_f32_16x16x32_bf16 v[12:15], v[140:143], v[208:211], v[12:15]
	s_setprio 0
	s_setprio 1
	v_mfma_f32_16x16x32_bf16 v[48:51], v[144:147], v[160:163], v[48:51]
	v_mfma_f32_16x16x32_bf16 v[52:55], v[152:155], v[160:163], v[52:55]
	v_mfma_f32_16x16x32_bf16 v[32:35], v[144:147], v[184:187], v[32:35]
	v_mfma_f32_16x16x32_bf16 v[36:39], v[152:155], v[184:187], v[36:39]
	v_mfma_f32_16x16x32_bf16 v[16:19], v[144:147], v[192:195], v[16:19]
	v_mfma_f32_16x16x32_bf16 v[20:23], v[152:155], v[192:195], v[20:23]
	v_mfma_f32_16x16x32_bf16 v[0:3], v[144:147], v[204:207], v[0:3]
	v_mfma_f32_16x16x32_bf16 v[4:7], v[152:155], v[204:207], v[4:7]
	v_mfma_f32_16x16x32_bf16 v[48:51], v[148:151], v[180:183], v[48:51]
	v_mfma_f32_16x16x32_bf16 v[52:55], v[156:159], v[180:183], v[52:55]
	v_mfma_f32_16x16x32_bf16 v[32:35], v[148:151], v[188:191], v[32:35]
	v_mfma_f32_16x16x32_bf16 v[36:39], v[156:159], v[188:191], v[36:39]
	s_setprio 2
	s_barrier
	v_mfma_f32_16x16x32_bf16 v[16:19], v[148:151], v[200:203], v[16:19]
	v_mfma_f32_16x16x32_bf16 v[20:23], v[156:159], v[200:203], v[20:23]
	v_mfma_f32_16x16x32_bf16 v[0:3], v[148:151], v[208:211], v[0:3]
	v_mfma_f32_16x16x32_bf16 v[4:7], v[156:159], v[208:211], v[4:7]
	s_setprio 0
	s_add_i32 s53, s53, 2
	s_add_u32 s51, s51, 0x100
	s_addc_u32 s52, s52, 0
	s_cmp_gt_u32 s53, 41
	s_mov_b64 s[24:25], s[4:5]
	s_cbranch_scc0 .LBB0_1310
